# adds: nt cache policy on the P3 (QM/KVM) and P8 (HID) epilogue stores
# speedup vs baseline: 1.0159x; 1.0101x over previous
; __device__ __forceinline__ unsigned cvt_pk_bf16(float lo, float hi) { unsigned r; asm volatile("v_cvt_pk_bf16_f32 %0, %1, %2" : "=v"(r) : "v"(lo), "v"(hi)); return r; }
; __device__ __forceinline__ float ssq_val(ssq_t v) { return (float)v * SSQ_IFX; }
;     __device__ __forceinline__ void operator()(const f32x4 (&acc)[2][2][4][2], const Unit& u, int wr, int wc, int fr, int fq) const {
;     ...
;         for (int i = 0; i < 8; ++i) rsv[i] = QS_B / sqrtf(ssq_val(sv[i]) * (1.0f / 384.0f) + EPS);
; #pragma unroll
;         for (int ai = 0; ai < 2; ++ai)
; #pragma unroll
;             for (int m = 0; m < 4; ++m) {
;                 const int row = row0 + ai * HALF + m * 16;
;                 const float rs = rsv[ai * 4 + m];
; #pragma unroll
;                 for (int bj = 0; bj < 2; ++bj) {
;                     const int colw = u.pn * BM + bj * HALF + wc * 32, col0 = colw + 8 * fq;
;                     const bool rope = (colw % 96) == 64 && colw < 576;
;                     f32x4 v0 = acc[ai][bj][m][0] * rs, v1 = acc[ai][bj][m][1] * rs;
;                     if (rope) {
;                         const float* tp = ropB + ((size_t)row * 16 + ((col0 - colw) >> 1)) * 2;
;                         const f32x4 c0 = *(const f32x4*)tp, c1 = *(const f32x4*)(tp + 4);
;                         f32x4 w0, w1;
;                         w0[0] = v0[0] * c0[0] - v0[1] * c0[1]; w0[1] = v0[1] * c0[0] + v0[0] * c0[1];
;                         w0[2] = v0[2] * c0[2] - v0[3] * c0[3]; w0[3] = v0[3] * c0[2] + v0[2] * c0[3];
;                         w1[0] = v1[0] * c1[0] - v1[1] * c1[1]; w1[1] = v1[1] * c1[0] + v1[0] * c1[1];
;                         w1[2] = v1[2] * c1[2] - v1[3] * c1[3]; w1[3] = v1[3] * c1[2] + v1[2] * c1[3];
;                         v0 = w0; v1 = w1;
;                     }
;                     u32x4 w; w.x = cvt_pk_bf16(v0[0], v0[1]); w.y = cvt_pk_bf16(v0[2], v0[3]); w.z = cvt_pk_bf16(v1[0], v1[1]); w.w = cvt_pk_bf16(v1[2], v1[3]);
;                     *(u32x4*)(O + (size_t)row * QMP + col0) = w;
;                 }
.LBB0_715:
	v_cvt_pk_bf16_f32 v166, v158, v159
	v_cvt_pk_bf16_f32 v167, v162, v163
	v_cvt_pk_bf16_f32 v168, v130, v131
	v_mov_b64_e32 v[130:131], s[16:17]
	v_mad_i64_i32 v[130:131], s[2:3], v140, s75, v[130:131]
	s_or_b32 s10, s30, 0x80
	s_mul_hi_i32 s2, s10, 0x2aaaaaab
	s_lshr_b32 s3, s2, 31
	s_lshr_b32 s2, s2, 4
	s_add_i32 s2, s2, s3
	s_mulk_i32 s2, 0x60
	s_sub_i32 s2, s10, s2
	s_cmp_eq_u32 s2, 64
	v_or_b32_e32 v128, s30, v0
	s_cselect_b64 s[2:3], -1, 0
	s_cmpk_lt_i32 s10, 0x240
	v_ashrrev_i32_e32 v129, 31, v128
	s_cselect_b64 s[10:11], -1, 0
	v_cvt_pk_bf16_f32 v169, v160, v161
	v_lshl_add_u64 v[158:159], v[128:129], 1, v[130:131]
	v_mov_b32_e32 v160, v156
	v_mov_b32_e32 v161, v156
	s_and_b64 s[2:3], s[10:11], s[2:3]
	v_mov_b32_e32 v157, v156
	global_store_dwordx4 v[158:159], v[166:169], off nt
	v_pk_mul_f32 v[158:159], v[124:125], v[160:161]
	v_pk_mul_f32 v[124:125], v[120:121], v[160:161]
	v_cndmask_b32_e64 v120, 0, 1, s[2:3]
	v_pk_mul_f32 v[122:123], v[122:123], v[156:157]
	v_cmp_ne_u32_e64 s[10:11], 1, v120
	s_andn2_b64 vcc, exec, s[2:3]
	v_pk_mul_f32 v[118:119], v[118:119], v[156:157]
	s_cbranch_vccnz .LBB0_717
	v_mov_b32_e32 v127, v1
	v_lshl_add_u64 v[120:121], v[132:133], 0, v[126:127]
	global_load_dwordx4 v[160:163], v[120:121], off
	global_load_dwordx4 v[166:169], v[120:121], off offset:16
	s_waitcnt vmcnt(0) lgkmcnt(0)
	v_pk_mul_f32 v[132:133], v[122:123], v[160:161] op_sel:[1,1] op_sel_hi:[0,1]
	v_pk_mul_f32 v[120:121], v[122:123], v[160:161]
	v_pk_fma_f32 v[122:123], v[122:123], v[160:161], v[132:133] op_sel_hi:[1,0,1]
	s_nop 0
	v_mul_f32_e32 v122, v159, v163
	v_pk_fma_f32 v[156:157], v[158:159], v[162:163], v[122:123] op_sel_hi:[1,1,0] neg_lo:[0,0,1] neg_hi:[0,0,1]
	v_mul_f32_e32 v122, v158, v163
	v_pk_fma_f32 v[160:161], v[158:159], v[162:163], v[122:123] op_sel:[1,0,0] op_sel_hi:[0,1,0]
	v_pk_mul_f32 v[162:163], v[118:119], v[166:167] op_sel:[1,1] op_sel_hi:[0,1]
	v_pk_mul_f32 v[158:159], v[118:119], v[166:167]
	v_pk_fma_f32 v[118:119], v[118:119], v[166:167], v[162:163] op_sel_hi:[1,0,1]
	v_sub_f32_e32 v122, v120, v132
	v_mul_f32_e32 v118, v125, v169
	v_pk_fma_f32 v[166:167], v[124:125], v[168:169], v[118:119] op_sel_hi:[1,1,0] neg_lo:[0,0,1] neg_hi:[0,0,1]
	v_mul_f32_e32 v118, v124, v169
	v_pk_fma_f32 v[168:169], v[124:125], v[168:169], v[118:119] op_sel:[1,0,0] op_sel_hi:[0,1,0]
	v_sub_f32_e32 v118, v158, v162
	v_mov_b32_e32 v158, v156
	v_mov_b32_e32 v159, v160
	v_mov_b32_e32 v124, v166
	v_mov_b32_e32 v125, v168
.LBB0_717:
	v_ffbh_u32_e32 v120, v155
	v_min_u32_e32 v127, 32, v120
	v_lshlrev_b64 v[120:121], v127, v[154:155]
	v_min_u32_e32 v120, 1, v120
	v_or_b32_e32 v120, v121, v120
	v_cvt_f32_u32_e32 v120, v120
	v_sub_u32_e32 v121, 32, v127
	s_ashr_i32 s31, s30, 31
	v_cvt_pk_bf16_f32 v154, v122, v123
	v_ldexp_f32 v120, v120, v121
	v_mul_f32_e32 v120, 0x33800000, v120
	v_fmamk_f32 v120, v120, 0x3b2aaaab, v226
	v_cvt_pk_bf16_f32 v155, v158, v159
	v_cvt_pk_bf16_f32 v156, v118, v119
	v_lshl_add_u64 v[118:119], v[0:1], 0, s[30:31]
	v_lshl_add_u64 v[122:123], v[118:119], 1, v[130:131]
	v_cvt_pk_bf16_f32 v157, v124, v125
	global_store_dwordx4 v[122:123], v[154:157], off offset:256 nt
	v_or_b32_e32 v122, 16, v140
	v_ashrrev_i32_e32 v123, 31, v122
	v_lshlrev_b64 v[130:131], 7, v[122:123]
	v_rsq_f32_e32 v120, v120
	s_nop 0
	v_mul_f32_e32 v120, s69, v120
	v_pk_mul_f32 v[124:125], v[116:117], v[120:121] op_sel_hi:[1,0]
	v_pk_mul_f32 v[114:115], v[114:115], v[120:121] op_sel_hi:[1,0]
	v_pk_mul_f32 v[116:117], v[112:113], v[120:121] op_sel_hi:[1,0]
	v_pk_mul_f32 v[110:111], v[110:111], v[120:121] op_sel_hi:[1,0]
	s_and_b64 vcc, exec, s[8:9]
	v_lshl_add_u64 v[112:113], s[20:21], 0, v[130:131]
	s_cbranch_vccnz .LBB0_719
	v_mov_b32_e32 v127, v1
	v_lshl_add_u64 v[154:155], v[112:113], 0, v[126:127]
	global_load_dwordx4 v[130:133], v[154:155], off
	s_nop 0
	global_load_dwordx4 v[154:157], v[154:155], off offset:16
	s_waitcnt vmcnt(0) lgkmcnt(0)
	v_pk_mul_f32 v[160:161], v[114:115], v[130:131] op_sel:[1,1] op_sel_hi:[0,1]
	v_mul_f32_e32 v0, v125, v133
	v_pk_mul_f32 v[158:159], v[114:115], v[130:131]
	v_pk_fma_f32 v[114:115], v[114:115], v[130:131], v[160:161] op_sel_hi:[1,0,1]
	v_pk_fma_f32 v[130:131], v[124:125], v[132:133], v[0:1] op_sel_hi:[1,1,0] neg_lo:[0,0,1] neg_hi:[0,0,1]
	v_mul_f32_e32 v0, v124, v133
	v_pk_fma_f32 v[132:133], v[124:125], v[132:133], v[0:1] op_sel:[1,0,0] op_sel_hi:[0,1,0]
	v_pk_mul_f32 v[162:163], v[110:111], v[154:155] op_sel:[1,1] op_sel_hi:[0,1]
	v_mul_f32_e32 v0, v117, v157
	v_pk_mul_f32 v[124:125], v[110:111], v[154:155]
	v_pk_fma_f32 v[110:111], v[110:111], v[154:155], v[162:163] op_sel_hi:[1,0,1]
	v_pk_fma_f32 v[154:155], v[116:117], v[156:157], v[0:1] op_sel_hi:[1,1,0] neg_lo:[0,0,1] neg_hi:[0,0,1]
	v_mul_f32_e32 v0, v116, v157
	v_pk_fma_f32 v[156:157], v[116:117], v[156:157], v[0:1] op_sel:[1,0,0] op_sel_hi:[0,1,0]
	v_sub_f32_e32 v114, v158, v160
	v_sub_f32_e32 v110, v124, v162
	v_mov_b32_e32 v124, v130
	v_mov_b32_e32 v125, v132
	v_mov_b32_e32 v116, v154
	v_mov_b32_e32 v117, v156
; __device__ __forceinline__ unsigned cvt_pk_bf16(float lo, float hi) { unsigned r; asm volatile("v_cvt_pk_bf16_f32 %0, %1, %2" : "=v"(r) : "v"(lo), "v"(hi)); return r; }
;     __device__ __forceinline__ void operator()(const f32x4 (&acc)[2][2][4][2], const Unit& u, int wr, int wc, int fr, int fq) const {
;     ...
;             for (int m = 0; m < 4; ++m) {
;                 const int row = row0 + ai * HALF + m * 16;
;                 const float rs = rsv[ai * 4 + m];
; #pragma unroll
;                 for (int bj = 0; bj < 2; ++bj) {
;                     const int colw = u.pn * BM + bj * HALF + wc * 32, col0 = colw + 8 * fq;
;                     const bool rope = (colw % 96) == 64 && colw < 576;
;                     f32x4 v0 = acc[ai][bj][m][0] * rs, v1 = acc[ai][bj][m][1] * rs;
;                     if (rope) {
;                         const float* tp = ropB + ((size_t)row * 16 + ((col0 - colw) >> 1)) * 2;
;                         const f32x4 c0 = *(const f32x4*)tp, c1 = *(const f32x4*)(tp + 4);
;                         f32x4 w0, w1;
;                         w0[0] = v0[0] * c0[0] - v0[1] * c0[1]; w0[1] = v0[1] * c0[0] + v0[0] * c0[1];
;                         w0[2] = v0[2] * c0[2] - v0[3] * c0[3]; w0[3] = v0[3] * c0[2] + v0[2] * c0[3];
;                         w1[0] = v1[0] * c1[0] - v1[1] * c1[1]; w1[1] = v1[1] * c1[0] + v1[0] * c1[1];
;                         w1[2] = v1[2] * c1[2] - v1[3] * c1[3]; w1[3] = v1[3] * c1[2] + v1[2] * c1[3];
;                         v0 = w0; v1 = w1;
;                     }
;                     u32x4 w; w.x = cvt_pk_bf16(v0[0], v0[1]); w.y = cvt_pk_bf16(v0[2], v0[3]); w.z = cvt_pk_bf16(v1[0], v1[1]); w.w = cvt_pk_bf16(v1[2], v1[3]);
;                     *(u32x4*)(O + (size_t)row * QMP + col0) = w;
;                 }
.LBB0_719:
	v_cvt_pk_bf16_f32 v130, v114, v115
	v_cvt_pk_bf16_f32 v131, v124, v125
	v_cvt_pk_bf16_f32 v132, v110, v111
	v_mov_b64_e32 v[110:111], s[16:17]
	v_mad_i64_i32 v[110:111], s[2:3], v122, s75, v[110:111]
	v_mov_b32_e32 v121, v120
	v_cvt_pk_bf16_f32 v133, v116, v117
	v_lshl_add_u64 v[114:115], v[128:129], 1, v[110:111]
	v_mov_b32_e32 v116, v120
	v_mov_b32_e32 v117, v120
	global_store_dwordx4 v[114:115], v[130:133], off nt
	v_pk_mul_f32 v[114:115], v[108:109], v[116:117]
	v_pk_mul_f32 v[106:107], v[106:107], v[120:121]
	v_pk_mul_f32 v[108:109], v[104:105], v[116:117]
	s_and_b64 vcc, exec, s[10:11]
	v_pk_mul_f32 v[102:103], v[102:103], v[120:121]
	s_cbranch_vccnz .LBB0_721
	v_mov_b32_e32 v127, v1
	v_lshl_add_u64 v[104:105], v[112:113], 0, v[126:127]
	global_load_dwordx4 v[120:123], v[104:105], off
	global_load_dwordx4 v[130:133], v[104:105], off offset:16
	s_waitcnt vmcnt(0) lgkmcnt(0)
	v_mul_f32_e32 v0, v115, v123
	v_pk_mul_f32 v[112:113], v[106:107], v[120:121] op_sel:[1,1] op_sel_hi:[0,1]
	v_pk_fma_f32 v[116:117], v[114:115], v[122:123], v[0:1] op_sel_hi:[1,1,0] neg_lo:[0,0,1] neg_hi:[0,0,1]
	v_mul_f32_e32 v0, v114, v123
	v_pk_mul_f32 v[104:105], v[106:107], v[120:121]
	v_pk_fma_f32 v[106:107], v[106:107], v[120:121], v[112:113] op_sel_hi:[1,0,1]
	v_pk_fma_f32 v[120:121], v[114:115], v[122:123], v[0:1] op_sel:[1,0,0] op_sel_hi:[0,1,0]
	v_mul_f32_e32 v0, v109, v133
	v_pk_mul_f32 v[122:123], v[102:103], v[130:131] op_sel:[1,1] op_sel_hi:[0,1]
	v_pk_fma_f32 v[124:125], v[108:109], v[132:133], v[0:1] op_sel_hi:[1,1,0] neg_lo:[0,0,1] neg_hi:[0,0,1]
	v_mul_f32_e32 v0, v108, v133
	v_pk_mul_f32 v[114:115], v[102:103], v[130:131]
	v_pk_fma_f32 v[102:103], v[102:103], v[130:131], v[122:123] op_sel_hi:[1,0,1]
	v_pk_fma_f32 v[130:131], v[108:109], v[132:133], v[0:1] op_sel:[1,0,0] op_sel_hi:[0,1,0]
	v_sub_f32_e32 v106, v104, v112
	v_sub_f32_e32 v102, v114, v122
	v_mov_b32_e32 v114, v116
	v_mov_b32_e32 v115, v120
	v_mov_b32_e32 v108, v124
	v_mov_b32_e32 v109, v130
.LBB0_721:
	v_ffbh_u32_e32 v0, v153
	v_min_u32_e32 v0, 32, v0
	v_lshlrev_b64 v[104:105], v0, v[152:153]
	v_min_u32_e32 v104, 1, v104
	v_or_b32_e32 v104, v105, v104
	v_cvt_f32_u32_e32 v104, v104
	v_sub_u32_e32 v0, 32, v0
	v_ldexp_f32 v0, v104, v0
	v_mul_f32_e32 v0, 0x33800000, v0
	v_fmamk_f32 v0, v0, 0x3b2aaaab, v226
	v_cvt_pk_bf16_f32 v112, v106, v107
	v_cvt_pk_bf16_f32 v113, v114, v115
	v_cvt_pk_bf16_f32 v114, v102, v103
	v_lshl_add_u64 v[102:103], v[118:119], 1, v[110:111]
	v_cvt_pk_bf16_f32 v115, v108, v109
	global_store_dwordx4 v[102:103], v[112:115], off offset:256 nt
	v_or_b32_e32 v102, 32, v140
	v_ashrrev_i32_e32 v103, 31, v102
	v_rsq_f32_e32 v104, v0
	s_nop 0
	v_mul_f32_e32 v104, s69, v104
	v_lshlrev_b64 v[108:109], 7, v[102:103]
	v_pk_mul_f32 v[106:107], v[100:101], v[104:105] op_sel_hi:[1,0]
	v_pk_mul_f32 v[98:99], v[98:99], v[104:105] op_sel_hi:[1,0]
	v_pk_mul_f32 v[100:101], v[96:97], v[104:105] op_sel_hi:[1,0]
	v_pk_mul_f32 v[94:95], v[94:95], v[104:105] op_sel_hi:[1,0]
	s_and_b64 vcc, exec, s[8:9]
	v_lshl_add_u64 v[96:97], s[20:21], 0, v[108:109]
	s_cbranch_vccnz .LBB0_723
	v_mov_b32_e32 v127, v1
	v_lshl_add_u64 v[112:113], v[96:97], 0, v[126:127]
	global_load_dwordx4 v[108:111], v[112:113], off
	s_nop 0
	global_load_dwordx4 v[112:115], v[112:113], off offset:16
	s_waitcnt vmcnt(0) lgkmcnt(0)
	v_pk_mul_f32 v[120:121], v[98:99], v[108:109] op_sel:[1,1] op_sel_hi:[0,1]
	v_mul_f32_e32 v0, v107, v111
	v_pk_mul_f32 v[116:117], v[98:99], v[108:109]
	v_pk_fma_f32 v[98:99], v[98:99], v[108:109], v[120:121] op_sel_hi:[1,0,1]
	v_pk_fma_f32 v[108:109], v[106:107], v[110:111], v[0:1] op_sel_hi:[1,1,0] neg_lo:[0,0,1] neg_hi:[0,0,1]
	v_mul_f32_e32 v0, v106, v111
	v_pk_fma_f32 v[110:111], v[106:107], v[110:111], v[0:1] op_sel:[1,0,0] op_sel_hi:[0,1,0]
	v_pk_mul_f32 v[122:123], v[94:95], v[112:113] op_sel:[1,1] op_sel_hi:[0,1]
	v_mul_f32_e32 v0, v101, v115
	v_pk_mul_f32 v[106:107], v[94:95], v[112:113]
	v_pk_fma_f32 v[94:95], v[94:95], v[112:113], v[122:123] op_sel_hi:[1,0,1]
	v_pk_fma_f32 v[112:113], v[100:101], v[114:115], v[0:1] op_sel_hi:[1,1,0] neg_lo:[0,0,1] neg_hi:[0,0,1]
	v_mul_f32_e32 v0, v100, v115
	v_pk_fma_f32 v[114:115], v[100:101], v[114:115], v[0:1] op_sel:[1,0,0] op_sel_hi:[0,1,0]
	v_sub_f32_e32 v98, v116, v120
	v_sub_f32_e32 v94, v106, v122
	v_mov_b32_e32 v106, v108
	v_mov_b32_e32 v107, v110
	v_mov_b32_e32 v100, v112
	v_mov_b32_e32 v101, v114
.LBB0_723:
	v_cvt_pk_bf16_f32 v108, v98, v99
	v_cvt_pk_bf16_f32 v109, v106, v107
	v_cvt_pk_bf16_f32 v110, v94, v95
	v_mov_b64_e32 v[94:95], s[16:17]
	v_mad_i64_i32 v[94:95], s[2:3], v102, s75, v[94:95]
	v_mov_b32_e32 v105, v104
	v_cvt_pk_bf16_f32 v111, v100, v101
	v_lshl_add_u64 v[98:99], v[128:129], 1, v[94:95]
	v_mov_b32_e32 v100, v104
	v_mov_b32_e32 v101, v104
	global_store_dwordx4 v[98:99], v[108:111], off nt
	v_pk_mul_f32 v[98:99], v[92:93], v[100:101]
	v_pk_mul_f32 v[90:91], v[90:91], v[104:105]
	v_pk_mul_f32 v[92:93], v[88:89], v[100:101]
	s_and_b64 vcc, exec, s[10:11]
	v_pk_mul_f32 v[86:87], v[86:87], v[104:105]
	s_cbranch_vccnz .LBB0_725
	v_mov_b32_e32 v127, v1
	v_lshl_add_u64 v[88:89], v[96:97], 0, v[126:127]
	global_load_dwordx4 v[100:103], v[88:89], off
	global_load_dwordx4 v[104:107], v[88:89], off offset:16
	s_waitcnt vmcnt(0) lgkmcnt(0)
	v_pk_mul_f32 v[96:97], v[90:91], v[100:101] op_sel:[1,1] op_sel_hi:[0,1]
	v_mul_f32_e32 v0, v99, v103
	v_pk_mul_f32 v[88:89], v[90:91], v[100:101]
	v_pk_fma_f32 v[90:91], v[90:91], v[100:101], v[96:97] op_sel_hi:[1,0,1]
	v_pk_fma_f32 v[100:101], v[98:99], v[102:103], v[0:1] op_sel_hi:[1,1,0] neg_lo:[0,0,1] neg_hi:[0,0,1]
	v_mul_f32_e32 v0, v98, v103
	v_pk_fma_f32 v[102:103], v[98:99], v[102:103], v[0:1] op_sel:[1,0,0] op_sel_hi:[0,1,0]
	v_pk_mul_f32 v[108:109], v[86:87], v[104:105] op_sel:[1,1] op_sel_hi:[0,1]
	v_mul_f32_e32 v0, v93, v107
	v_pk_mul_f32 v[98:99], v[86:87], v[104:105]
	v_pk_fma_f32 v[86:87], v[86:87], v[104:105], v[108:109] op_sel_hi:[1,0,1]
	v_pk_fma_f32 v[104:105], v[92:93], v[106:107], v[0:1] op_sel_hi:[1,1,0] neg_lo:[0,0,1] neg_hi:[0,0,1]
	v_mul_f32_e32 v0, v92, v107
	v_pk_fma_f32 v[106:107], v[92:93], v[106:107], v[0:1] op_sel:[1,0,0] op_sel_hi:[0,1,0]
	v_sub_f32_e32 v90, v88, v96
	v_sub_f32_e32 v86, v98, v108
	v_mov_b32_e32 v98, v100
	v_mov_b32_e32 v99, v102
	v_mov_b32_e32 v92, v104
	v_mov_b32_e32 v93, v106
; __device__ __forceinline__ unsigned cvt_pk_bf16(float lo, float hi) { unsigned r; asm volatile("v_cvt_pk_bf16_f32 %0, %1, %2" : "=v"(r) : "v"(lo), "v"(hi)); return r; }
;     __device__ __forceinline__ void operator()(const f32x4 (&acc)[2][2][4][2], const Unit& u, int wr, int wc, int fr, int fq) const {
;     ...
;             for (int m = 0; m < 4; ++m) {
;                 const int row = row0 + ai * HALF + m * 16;
;                 const float rs = rsv[ai * 4 + m];
; #pragma unroll
;                 for (int bj = 0; bj < 2; ++bj) {
;                     const int colw = u.pn * BM + bj * HALF + wc * 32, col0 = colw + 8 * fq;
;                     const bool rope = (colw % 96) == 64 && colw < 576;
;                     f32x4 v0 = acc[ai][bj][m][0] * rs, v1 = acc[ai][bj][m][1] * rs;
;                     if (rope) {
;                         const float* tp = ropB + ((size_t)row * 16 + ((col0 - colw) >> 1)) * 2;
;                         const f32x4 c0 = *(const f32x4*)tp, c1 = *(const f32x4*)(tp + 4);
;                         f32x4 w0, w1;
;                         w0[0] = v0[0] * c0[0] - v0[1] * c0[1]; w0[1] = v0[1] * c0[0] + v0[0] * c0[1];
;                         w0[2] = v0[2] * c0[2] - v0[3] * c0[3]; w0[3] = v0[3] * c0[2] + v0[2] * c0[3];
;                         w1[0] = v1[0] * c1[0] - v1[1] * c1[1]; w1[1] = v1[1] * c1[0] + v1[0] * c1[1];
;                         w1[2] = v1[2] * c1[2] - v1[3] * c1[3]; w1[3] = v1[3] * c1[2] + v1[2] * c1[3];
;                         v0 = w0; v1 = w1;
;                     }
;                     u32x4 w; w.x = cvt_pk_bf16(v0[0], v0[1]); w.y = cvt_pk_bf16(v0[2], v0[3]); w.z = cvt_pk_bf16(v1[0], v1[1]); w.w = cvt_pk_bf16(v1[2], v1[3]);
;                     *(u32x4*)(O + (size_t)row * QMP + col0) = w;
;                 }
.LBB0_725:
	v_ffbh_u32_e32 v0, v151
	v_min_u32_e32 v0, 32, v0
	v_lshlrev_b64 v[88:89], v0, v[150:151]
	v_min_u32_e32 v88, 1, v88
	v_or_b32_e32 v88, v89, v88
	v_cvt_f32_u32_e32 v88, v88
	v_sub_u32_e32 v0, 32, v0
	v_ldexp_f32 v0, v88, v0
	v_mul_f32_e32 v0, 0x33800000, v0
	v_fmamk_f32 v0, v0, 0x3b2aaaab, v226
	v_cvt_pk_bf16_f32 v96, v90, v91
	v_cvt_pk_bf16_f32 v97, v98, v99
	v_cvt_pk_bf16_f32 v98, v86, v87
	v_lshl_add_u64 v[86:87], v[118:119], 1, v[94:95]
	v_cvt_pk_bf16_f32 v99, v92, v93
	global_store_dwordx4 v[86:87], v[96:99], off offset:256 nt
	v_or_b32_e32 v86, 48, v140
	v_ashrrev_i32_e32 v87, 31, v86
	v_rsq_f32_e32 v88, v0
	s_nop 0
	v_mul_f32_e32 v88, s69, v88
	v_lshlrev_b64 v[92:93], 7, v[86:87]
	v_pk_mul_f32 v[90:91], v[84:85], v[88:89] op_sel_hi:[1,0]
	v_pk_mul_f32 v[82:83], v[82:83], v[88:89] op_sel_hi:[1,0]
	v_pk_mul_f32 v[84:85], v[80:81], v[88:89] op_sel_hi:[1,0]
	v_pk_mul_f32 v[78:79], v[78:79], v[88:89] op_sel_hi:[1,0]
	s_and_b64 vcc, exec, s[8:9]
	v_lshl_add_u64 v[80:81], s[20:21], 0, v[92:93]
	s_cbranch_vccnz .LBB0_727
	v_mov_b32_e32 v127, v1
	v_lshl_add_u64 v[96:97], v[80:81], 0, v[126:127]
	global_load_dwordx4 v[92:95], v[96:97], off
	s_nop 0
	global_load_dwordx4 v[96:99], v[96:97], off offset:16
	s_waitcnt vmcnt(0) lgkmcnt(0)
	v_pk_mul_f32 v[102:103], v[82:83], v[92:93] op_sel:[1,1] op_sel_hi:[0,1]
	v_mul_f32_e32 v0, v91, v95
	v_pk_mul_f32 v[100:101], v[82:83], v[92:93]
	v_pk_fma_f32 v[82:83], v[82:83], v[92:93], v[102:103] op_sel_hi:[1,0,1]
	v_pk_fma_f32 v[92:93], v[90:91], v[94:95], v[0:1] op_sel_hi:[1,1,0] neg_lo:[0,0,1] neg_hi:[0,0,1]
	v_mul_f32_e32 v0, v90, v95
	v_pk_fma_f32 v[94:95], v[90:91], v[94:95], v[0:1] op_sel:[1,0,0] op_sel_hi:[0,1,0]
	v_pk_mul_f32 v[104:105], v[78:79], v[96:97] op_sel:[1,1] op_sel_hi:[0,1]
	v_mul_f32_e32 v0, v85, v99
	v_pk_mul_f32 v[90:91], v[78:79], v[96:97]
	v_pk_fma_f32 v[78:79], v[78:79], v[96:97], v[104:105] op_sel_hi:[1,0,1]
	v_pk_fma_f32 v[96:97], v[84:85], v[98:99], v[0:1] op_sel_hi:[1,1,0] neg_lo:[0,0,1] neg_hi:[0,0,1]
	v_mul_f32_e32 v0, v84, v99
	v_pk_fma_f32 v[98:99], v[84:85], v[98:99], v[0:1] op_sel:[1,0,0] op_sel_hi:[0,1,0]
	v_sub_f32_e32 v82, v100, v102
	v_sub_f32_e32 v78, v90, v104
	v_mov_b32_e32 v90, v92
	v_mov_b32_e32 v91, v94
	v_mov_b32_e32 v84, v96
	v_mov_b32_e32 v85, v98
.LBB0_727:
	v_cvt_pk_bf16_f32 v92, v82, v83
	v_cvt_pk_bf16_f32 v93, v90, v91
	v_cvt_pk_bf16_f32 v94, v78, v79
	v_mov_b64_e32 v[78:79], s[16:17]
	v_mad_i64_i32 v[78:79], s[2:3], v86, s75, v[78:79]
	v_mov_b32_e32 v89, v88
	v_cvt_pk_bf16_f32 v95, v84, v85
	v_lshl_add_u64 v[82:83], v[128:129], 1, v[78:79]
	v_mov_b32_e32 v84, v88
	v_mov_b32_e32 v85, v88
	global_store_dwordx4 v[82:83], v[92:95], off nt
	v_pk_mul_f32 v[82:83], v[76:77], v[84:85]
	v_pk_mul_f32 v[74:75], v[74:75], v[88:89]
	v_pk_mul_f32 v[72:73], v[72:73], v[84:85]
	s_and_b64 vcc, exec, s[10:11]
	v_pk_mul_f32 v[70:71], v[70:71], v[88:89]
	s_cbranch_vccnz .LBB0_729
	v_mov_b32_e32 v127, v1
	v_lshl_add_u64 v[76:77], v[80:81], 0, v[126:127]
	global_load_dwordx4 v[84:87], v[76:77], off
	global_load_dwordx4 v[88:91], v[76:77], off offset:16
	s_waitcnt vmcnt(0) lgkmcnt(0)
	v_pk_mul_f32 v[80:81], v[74:75], v[84:85] op_sel:[1,1] op_sel_hi:[0,1]
	v_mul_f32_e32 v0, v83, v87
	v_pk_mul_f32 v[76:77], v[74:75], v[84:85]
	v_pk_fma_f32 v[74:75], v[74:75], v[84:85], v[80:81] op_sel_hi:[1,0,1]
	v_pk_fma_f32 v[84:85], v[82:83], v[86:87], v[0:1] op_sel_hi:[1,1,0] neg_lo:[0,0,1] neg_hi:[0,0,1]
	v_mul_f32_e32 v0, v82, v87
	v_pk_fma_f32 v[86:87], v[82:83], v[86:87], v[0:1] op_sel:[1,0,0] op_sel_hi:[0,1,0]
	v_pk_mul_f32 v[92:93], v[70:71], v[88:89] op_sel:[1,1] op_sel_hi:[0,1]
	v_mul_f32_e32 v0, v73, v91
	v_pk_mul_f32 v[82:83], v[70:71], v[88:89]
	v_pk_fma_f32 v[70:71], v[70:71], v[88:89], v[92:93] op_sel_hi:[1,0,1]
	v_pk_fma_f32 v[88:89], v[72:73], v[90:91], v[0:1] op_sel_hi:[1,1,0] neg_lo:[0,0,1] neg_hi:[0,0,1]
	v_mul_f32_e32 v0, v72, v91
	v_pk_fma_f32 v[90:91], v[72:73], v[90:91], v[0:1] op_sel:[1,0,0] op_sel_hi:[0,1,0]
	v_sub_f32_e32 v74, v76, v80
	v_sub_f32_e32 v70, v82, v92
	v_mov_b32_e32 v82, v84
	v_mov_b32_e32 v83, v86
	v_mov_b32_e32 v72, v88
	v_mov_b32_e32 v73, v90
.LBB0_729:
	v_ffbh_u32_e32 v0, v149
	v_min_u32_e32 v0, 32, v0
	v_lshlrev_b64 v[76:77], v0, v[148:149]
	v_min_u32_e32 v76, 1, v76
	v_or_b32_e32 v76, v77, v76
	v_cvt_f32_u32_e32 v76, v76
	v_sub_u32_e32 v0, 32, v0
	v_ldexp_f32 v0, v76, v0
	v_mul_f32_e32 v0, 0x33800000, v0
	v_fmamk_f32 v0, v0, 0x3b2aaaab, v226
	v_add_u32_e32 v80, 0x80, v140
	v_ashrrev_i32_e32 v81, 31, v80
	v_rsq_f32_e32 v76, v0
	s_nop 0
	v_mul_f32_e32 v76, s69, v76
	v_cvt_pk_bf16_f32 v84, v74, v75
	v_cvt_pk_bf16_f32 v85, v82, v83
	v_cvt_pk_bf16_f32 v86, v70, v71
	v_cvt_pk_bf16_f32 v87, v72, v73
	v_lshl_add_u64 v[70:71], v[118:119], 1, v[78:79]
	v_lshlrev_b64 v[72:73], 7, v[80:81]
	global_store_dwordx4 v[70:71], v[84:87], off offset:256 nt
	v_pk_mul_f32 v[70:71], v[68:69], v[76:77] op_sel_hi:[1,0]
	v_pk_mul_f32 v[66:67], v[66:67], v[76:77] op_sel_hi:[1,0]
	v_pk_mul_f32 v[68:69], v[64:65], v[76:77] op_sel_hi:[1,0]
	v_pk_mul_f32 v[62:63], v[62:63], v[76:77] op_sel_hi:[1,0]
	s_and_b64 vcc, exec, s[8:9]
	v_lshl_add_u64 v[64:65], s[20:21], 0, v[72:73]
	s_cbranch_vccnz .LBB0_731
	v_mov_b32_e32 v127, v1
	v_lshl_add_u64 v[78:79], v[64:65], 0, v[126:127]
	global_load_dwordx4 v[72:75], v[78:79], off
	global_load_dwordx4 v[82:85], v[78:79], off offset:16
	s_waitcnt vmcnt(0) lgkmcnt(0)
	v_pk_mul_f32 v[86:87], v[66:67], v[72:73] op_sel:[1,1] op_sel_hi:[0,1]
	v_mul_f32_e32 v0, v71, v75
	v_pk_mul_f32 v[78:79], v[66:67], v[72:73]
	v_pk_fma_f32 v[66:67], v[66:67], v[72:73], v[86:87] op_sel_hi:[1,0,1]
	v_pk_fma_f32 v[72:73], v[70:71], v[74:75], v[0:1] op_sel_hi:[1,1,0] neg_lo:[0,0,1] neg_hi:[0,0,1]
	v_mul_f32_e32 v0, v70, v75
	v_pk_fma_f32 v[74:75], v[70:71], v[74:75], v[0:1] op_sel:[1,0,0] op_sel_hi:[0,1,0]
	v_pk_mul_f32 v[88:89], v[62:63], v[82:83] op_sel:[1,1] op_sel_hi:[0,1]
	v_mul_f32_e32 v0, v69, v85
	v_pk_mul_f32 v[70:71], v[62:63], v[82:83]
	v_pk_fma_f32 v[62:63], v[62:63], v[82:83], v[88:89] op_sel_hi:[1,0,1]
	v_pk_fma_f32 v[82:83], v[68:69], v[84:85], v[0:1] op_sel_hi:[1,1,0] neg_lo:[0,0,1] neg_hi:[0,0,1]
	v_mul_f32_e32 v0, v68, v85
	v_pk_fma_f32 v[84:85], v[68:69], v[84:85], v[0:1] op_sel:[1,0,0] op_sel_hi:[0,1,0]
	v_sub_f32_e32 v66, v78, v86
	v_sub_f32_e32 v62, v70, v88
	v_mov_b32_e32 v70, v72
	v_mov_b32_e32 v71, v74
	v_mov_b32_e32 v68, v82
	v_mov_b32_e32 v69, v84
; __device__ __forceinline__ unsigned cvt_pk_bf16(float lo, float hi) { unsigned r; asm volatile("v_cvt_pk_bf16_f32 %0, %1, %2" : "=v"(r) : "v"(lo), "v"(hi)); return r; }
;     __device__ __forceinline__ void operator()(const f32x4 (&acc)[2][2][4][2], const Unit& u, int wr, int wc, int fr, int fq) const {
;     ...
;             for (int m = 0; m < 4; ++m) {
;                 const int row = row0 + ai * HALF + m * 16;
;                 const float rs = rsv[ai * 4 + m];
; #pragma unroll
;                 for (int bj = 0; bj < 2; ++bj) {
;                     const int colw = u.pn * BM + bj * HALF + wc * 32, col0 = colw + 8 * fq;
;                     const bool rope = (colw % 96) == 64 && colw < 576;
;                     f32x4 v0 = acc[ai][bj][m][0] * rs, v1 = acc[ai][bj][m][1] * rs;
;                     if (rope) {
;                         const float* tp = ropB + ((size_t)row * 16 + ((col0 - colw) >> 1)) * 2;
;                         const f32x4 c0 = *(const f32x4*)tp, c1 = *(const f32x4*)(tp + 4);
;                         f32x4 w0, w1;
;                         w0[0] = v0[0] * c0[0] - v0[1] * c0[1]; w0[1] = v0[1] * c0[0] + v0[0] * c0[1];
;                         w0[2] = v0[2] * c0[2] - v0[3] * c0[3]; w0[3] = v0[3] * c0[2] + v0[2] * c0[3];
;                         w1[0] = v1[0] * c1[0] - v1[1] * c1[1]; w1[1] = v1[1] * c1[0] + v1[0] * c1[1];
;                         w1[2] = v1[2] * c1[2] - v1[3] * c1[3]; w1[3] = v1[3] * c1[2] + v1[2] * c1[3];
;                         v0 = w0; v1 = w1;
;                     }
;                     u32x4 w; w.x = cvt_pk_bf16(v0[0], v0[1]); w.y = cvt_pk_bf16(v0[2], v0[3]); w.z = cvt_pk_bf16(v1[0], v1[1]); w.w = cvt_pk_bf16(v1[2], v1[3]);
;                     *(u32x4*)(O + (size_t)row * QMP + col0) = w;
;                 }
.LBB0_731:
	v_cvt_pk_bf16_f32 v72, v66, v67
	v_cvt_pk_bf16_f32 v73, v70, v71
	v_cvt_pk_bf16_f32 v74, v62, v63
	v_mov_b64_e32 v[62:63], s[16:17]
	v_mad_i64_i32 v[62:63], s[2:3], v80, s75, v[62:63]
	v_mov_b32_e32 v77, v76
	v_cvt_pk_bf16_f32 v75, v68, v69
	v_lshl_add_u64 v[66:67], v[128:129], 1, v[62:63]
	v_mov_b32_e32 v68, v76
	v_mov_b32_e32 v69, v76
	global_store_dwordx4 v[66:67], v[72:75], off nt
	v_pk_mul_f32 v[66:67], v[60:61], v[68:69]
	v_pk_mul_f32 v[58:59], v[58:59], v[76:77]
	v_pk_mul_f32 v[60:61], v[56:57], v[68:69]
	s_and_b64 vcc, exec, s[10:11]
	v_pk_mul_f32 v[54:55], v[54:55], v[76:77]
	s_cbranch_vccnz .LBB0_733
	v_mov_b32_e32 v127, v1
	v_lshl_add_u64 v[56:57], v[64:65], 0, v[126:127]
	global_load_dwordx4 v[68:71], v[56:57], off
	global_load_dwordx4 v[72:75], v[56:57], off offset:16
	s_waitcnt vmcnt(0) lgkmcnt(0)
	v_pk_mul_f32 v[64:65], v[58:59], v[68:69] op_sel:[1,1] op_sel_hi:[0,1]
	v_mul_f32_e32 v0, v67, v71
	v_pk_mul_f32 v[56:57], v[58:59], v[68:69]
	v_pk_fma_f32 v[58:59], v[58:59], v[68:69], v[64:65] op_sel_hi:[1,0,1]
	v_pk_fma_f32 v[68:69], v[66:67], v[70:71], v[0:1] op_sel_hi:[1,1,0] neg_lo:[0,0,1] neg_hi:[0,0,1]
	v_mul_f32_e32 v0, v66, v71
	v_pk_fma_f32 v[70:71], v[66:67], v[70:71], v[0:1] op_sel:[1,0,0] op_sel_hi:[0,1,0]
	v_pk_mul_f32 v[76:77], v[54:55], v[72:73] op_sel:[1,1] op_sel_hi:[0,1]
	v_mul_f32_e32 v0, v61, v75
	v_pk_mul_f32 v[66:67], v[54:55], v[72:73]
	v_pk_fma_f32 v[54:55], v[54:55], v[72:73], v[76:77] op_sel_hi:[1,0,1]
	v_pk_fma_f32 v[72:73], v[60:61], v[74:75], v[0:1] op_sel_hi:[1,1,0] neg_lo:[0,0,1] neg_hi:[0,0,1]
	v_mul_f32_e32 v0, v60, v75
	v_pk_fma_f32 v[74:75], v[60:61], v[74:75], v[0:1] op_sel:[1,0,0] op_sel_hi:[0,1,0]
	v_sub_f32_e32 v58, v56, v64
	v_sub_f32_e32 v54, v66, v76
	v_mov_b32_e32 v66, v68
	v_mov_b32_e32 v67, v70
	v_mov_b32_e32 v60, v72
	v_mov_b32_e32 v61, v74
.LBB0_733:
	v_ffbh_u32_e32 v0, v147
	v_min_u32_e32 v0, 32, v0
	v_lshlrev_b64 v[56:57], v0, v[146:147]
	v_min_u32_e32 v56, 1, v56
	v_or_b32_e32 v56, v57, v56
	v_cvt_f32_u32_e32 v56, v56
	v_sub_u32_e32 v0, 32, v0
	v_ldexp_f32 v0, v56, v0
	v_mul_f32_e32 v0, 0x33800000, v0
	v_fmamk_f32 v0, v0, 0x3b2aaaab, v226
	v_cvt_pk_bf16_f32 v64, v58, v59
	v_cvt_pk_bf16_f32 v65, v66, v67
	v_cvt_pk_bf16_f32 v66, v54, v55
	v_lshl_add_u64 v[54:55], v[118:119], 1, v[62:63]
	v_cvt_pk_bf16_f32 v67, v60, v61
	global_store_dwordx4 v[54:55], v[64:67], off offset:256 nt
	v_add_u32_e32 v54, 0x90, v140
	v_ashrrev_i32_e32 v55, 31, v54
	v_rsq_f32_e32 v56, v0
	s_nop 0
	v_mul_f32_e32 v56, s69, v56
	v_lshlrev_b64 v[60:61], 7, v[54:55]
	v_pk_mul_f32 v[58:59], v[52:53], v[56:57] op_sel_hi:[1,0]
	v_pk_mul_f32 v[50:51], v[50:51], v[56:57] op_sel_hi:[1,0]
	v_pk_mul_f32 v[52:53], v[48:49], v[56:57] op_sel_hi:[1,0]
	v_pk_mul_f32 v[46:47], v[46:47], v[56:57] op_sel_hi:[1,0]
	s_and_b64 vcc, exec, s[8:9]
	v_lshl_add_u64 v[48:49], s[20:21], 0, v[60:61]
	s_cbranch_vccnz .LBB0_735
	v_mov_b32_e32 v127, v1
	v_lshl_add_u64 v[64:65], v[48:49], 0, v[126:127]
	global_load_dwordx4 v[60:63], v[64:65], off
	s_nop 0
	global_load_dwordx4 v[64:67], v[64:65], off offset:16
	s_waitcnt vmcnt(0) lgkmcnt(0)
	v_pk_mul_f32 v[70:71], v[50:51], v[60:61] op_sel:[1,1] op_sel_hi:[0,1]
	v_mul_f32_e32 v0, v59, v63
	v_pk_mul_f32 v[68:69], v[50:51], v[60:61]
	v_pk_fma_f32 v[50:51], v[50:51], v[60:61], v[70:71] op_sel_hi:[1,0,1]
	v_pk_fma_f32 v[60:61], v[58:59], v[62:63], v[0:1] op_sel_hi:[1,1,0] neg_lo:[0,0,1] neg_hi:[0,0,1]
	v_mul_f32_e32 v0, v58, v63
	v_pk_fma_f32 v[62:63], v[58:59], v[62:63], v[0:1] op_sel:[1,0,0] op_sel_hi:[0,1,0]
	v_pk_mul_f32 v[72:73], v[46:47], v[64:65] op_sel:[1,1] op_sel_hi:[0,1]
	v_mul_f32_e32 v0, v53, v67
	v_pk_mul_f32 v[58:59], v[46:47], v[64:65]
	v_pk_fma_f32 v[46:47], v[46:47], v[64:65], v[72:73] op_sel_hi:[1,0,1]
	v_pk_fma_f32 v[64:65], v[52:53], v[66:67], v[0:1] op_sel_hi:[1,1,0] neg_lo:[0,0,1] neg_hi:[0,0,1]
	v_mul_f32_e32 v0, v52, v67
	v_pk_fma_f32 v[66:67], v[52:53], v[66:67], v[0:1] op_sel:[1,0,0] op_sel_hi:[0,1,0]
	v_sub_f32_e32 v50, v68, v70
	v_sub_f32_e32 v46, v58, v72
	v_mov_b32_e32 v58, v60
	v_mov_b32_e32 v59, v62
	v_mov_b32_e32 v52, v64
	v_mov_b32_e32 v53, v66
.LBB0_735:
	v_cvt_pk_bf16_f32 v60, v50, v51
	v_cvt_pk_bf16_f32 v61, v58, v59
	v_cvt_pk_bf16_f32 v62, v46, v47
	v_mov_b64_e32 v[46:47], s[16:17]
	v_mad_i64_i32 v[46:47], s[2:3], v54, s75, v[46:47]
	v_mov_b32_e32 v57, v56
	v_cvt_pk_bf16_f32 v63, v52, v53
	v_lshl_add_u64 v[50:51], v[128:129], 1, v[46:47]
	v_mov_b32_e32 v52, v56
	v_mov_b32_e32 v53, v56
	global_store_dwordx4 v[50:51], v[60:63], off nt
	v_pk_mul_f32 v[50:51], v[44:45], v[52:53]
	v_pk_mul_f32 v[42:43], v[42:43], v[56:57]
	v_pk_mul_f32 v[44:45], v[40:41], v[52:53]
	s_and_b64 vcc, exec, s[10:11]
	v_pk_mul_f32 v[38:39], v[38:39], v[56:57]
	s_cbranch_vccnz .LBB0_737
	v_mov_b32_e32 v127, v1
	v_lshl_add_u64 v[40:41], v[48:49], 0, v[126:127]
	global_load_dwordx4 v[52:55], v[40:41], off
	global_load_dwordx4 v[56:59], v[40:41], off offset:16
	s_waitcnt vmcnt(0) lgkmcnt(0)
	v_pk_mul_f32 v[48:49], v[42:43], v[52:53] op_sel:[1,1] op_sel_hi:[0,1]
	v_mul_f32_e32 v0, v51, v55
	v_pk_mul_f32 v[40:41], v[42:43], v[52:53]
	v_pk_fma_f32 v[42:43], v[42:43], v[52:53], v[48:49] op_sel_hi:[1,0,1]
	v_pk_fma_f32 v[52:53], v[50:51], v[54:55], v[0:1] op_sel_hi:[1,1,0] neg_lo:[0,0,1] neg_hi:[0,0,1]
	v_mul_f32_e32 v0, v50, v55
	v_pk_fma_f32 v[54:55], v[50:51], v[54:55], v[0:1] op_sel:[1,0,0] op_sel_hi:[0,1,0]
	v_pk_mul_f32 v[60:61], v[38:39], v[56:57] op_sel:[1,1] op_sel_hi:[0,1]
	v_mul_f32_e32 v0, v45, v59
	v_pk_mul_f32 v[50:51], v[38:39], v[56:57]
	v_pk_fma_f32 v[38:39], v[38:39], v[56:57], v[60:61] op_sel_hi:[1,0,1]
	v_pk_fma_f32 v[56:57], v[44:45], v[58:59], v[0:1] op_sel_hi:[1,1,0] neg_lo:[0,0,1] neg_hi:[0,0,1]
	v_mul_f32_e32 v0, v44, v59
	v_pk_fma_f32 v[58:59], v[44:45], v[58:59], v[0:1] op_sel:[1,0,0] op_sel_hi:[0,1,0]
	v_sub_f32_e32 v42, v40, v48
	v_sub_f32_e32 v38, v50, v60
	v_mov_b32_e32 v50, v52
	v_mov_b32_e32 v51, v54
	v_mov_b32_e32 v44, v56
	v_mov_b32_e32 v45, v58
; __device__ __forceinline__ unsigned cvt_pk_bf16(float lo, float hi) { unsigned r; asm volatile("v_cvt_pk_bf16_f32 %0, %1, %2" : "=v"(r) : "v"(lo), "v"(hi)); return r; }
;     __device__ __forceinline__ void operator()(const f32x4 (&acc)[2][2][4][2], const Unit& u, int wr, int wc, int fr, int fq) const {
;     ...
;             for (int m = 0; m < 4; ++m) {
;                 const int row = row0 + ai * HALF + m * 16;
;                 const float rs = rsv[ai * 4 + m];
; #pragma unroll
;                 for (int bj = 0; bj < 2; ++bj) {
;                     const int colw = u.pn * BM + bj * HALF + wc * 32, col0 = colw + 8 * fq;
;                     const bool rope = (colw % 96) == 64 && colw < 576;
;                     f32x4 v0 = acc[ai][bj][m][0] * rs, v1 = acc[ai][bj][m][1] * rs;
;                     if (rope) {
;                         const float* tp = ropB + ((size_t)row * 16 + ((col0 - colw) >> 1)) * 2;
;                         const f32x4 c0 = *(const f32x4*)tp, c1 = *(const f32x4*)(tp + 4);
;                         f32x4 w0, w1;
;                         w0[0] = v0[0] * c0[0] - v0[1] * c0[1]; w0[1] = v0[1] * c0[0] + v0[0] * c0[1];
;                         w0[2] = v0[2] * c0[2] - v0[3] * c0[3]; w0[3] = v0[3] * c0[2] + v0[2] * c0[3];
;                         w1[0] = v1[0] * c1[0] - v1[1] * c1[1]; w1[1] = v1[1] * c1[0] + v1[0] * c1[1];
;                         w1[2] = v1[2] * c1[2] - v1[3] * c1[3]; w1[3] = v1[3] * c1[2] + v1[2] * c1[3];
;                         v0 = w0; v1 = w1;
;                     }
;                     u32x4 w; w.x = cvt_pk_bf16(v0[0], v0[1]); w.y = cvt_pk_bf16(v0[2], v0[3]); w.z = cvt_pk_bf16(v1[0], v1[1]); w.w = cvt_pk_bf16(v1[2], v1[3]);
;                     *(u32x4*)(O + (size_t)row * QMP + col0) = w;
;                 }
.LBB0_737:
	v_ffbh_u32_e32 v0, v145
	v_min_u32_e32 v0, 32, v0
	v_lshlrev_b64 v[40:41], v0, v[144:145]
	v_min_u32_e32 v40, 1, v40
	v_or_b32_e32 v40, v41, v40
	v_cvt_f32_u32_e32 v40, v40
	v_sub_u32_e32 v0, 32, v0
	v_ldexp_f32 v0, v40, v0
	v_mul_f32_e32 v0, 0x33800000, v0
	v_fmamk_f32 v0, v0, 0x3b2aaaab, v226
	v_cvt_pk_bf16_f32 v48, v42, v43
	v_cvt_pk_bf16_f32 v49, v50, v51
	v_cvt_pk_bf16_f32 v50, v38, v39
	v_lshl_add_u64 v[38:39], v[118:119], 1, v[46:47]
	v_cvt_pk_bf16_f32 v51, v44, v45
	global_store_dwordx4 v[38:39], v[48:51], off offset:256 nt
	v_add_u32_e32 v38, 0xa0, v140
	v_ashrrev_i32_e32 v39, 31, v38
	v_rsq_f32_e32 v40, v0
	s_nop 0
	v_mul_f32_e32 v40, s69, v40
	v_lshlrev_b64 v[44:45], 7, v[38:39]
	v_pk_mul_f32 v[42:43], v[36:37], v[40:41] op_sel_hi:[1,0]
	v_pk_mul_f32 v[34:35], v[34:35], v[40:41] op_sel_hi:[1,0]
	v_pk_mul_f32 v[36:37], v[32:33], v[40:41] op_sel_hi:[1,0]
	v_pk_mul_f32 v[30:31], v[30:31], v[40:41] op_sel_hi:[1,0]
	s_and_b64 vcc, exec, s[8:9]
	v_lshl_add_u64 v[32:33], s[20:21], 0, v[44:45]
	s_cbranch_vccnz .LBB0_739
	v_mov_b32_e32 v127, v1
	v_lshl_add_u64 v[48:49], v[32:33], 0, v[126:127]
	global_load_dwordx4 v[44:47], v[48:49], off
	s_nop 0
	global_load_dwordx4 v[48:51], v[48:49], off offset:16
	s_waitcnt vmcnt(0) lgkmcnt(0)
	v_pk_mul_f32 v[54:55], v[34:35], v[44:45] op_sel:[1,1] op_sel_hi:[0,1]
	v_mul_f32_e32 v0, v43, v47
	v_pk_mul_f32 v[52:53], v[34:35], v[44:45]
	v_pk_fma_f32 v[34:35], v[34:35], v[44:45], v[54:55] op_sel_hi:[1,0,1]
	v_pk_fma_f32 v[44:45], v[42:43], v[46:47], v[0:1] op_sel_hi:[1,1,0] neg_lo:[0,0,1] neg_hi:[0,0,1]
	v_mul_f32_e32 v0, v42, v47
	v_pk_fma_f32 v[46:47], v[42:43], v[46:47], v[0:1] op_sel:[1,0,0] op_sel_hi:[0,1,0]
	v_pk_mul_f32 v[56:57], v[30:31], v[48:49] op_sel:[1,1] op_sel_hi:[0,1]
	v_mul_f32_e32 v0, v37, v51
	v_pk_mul_f32 v[42:43], v[30:31], v[48:49]
	v_pk_fma_f32 v[30:31], v[30:31], v[48:49], v[56:57] op_sel_hi:[1,0,1]
	v_pk_fma_f32 v[48:49], v[36:37], v[50:51], v[0:1] op_sel_hi:[1,1,0] neg_lo:[0,0,1] neg_hi:[0,0,1]
	v_mul_f32_e32 v0, v36, v51
	v_pk_fma_f32 v[50:51], v[36:37], v[50:51], v[0:1] op_sel:[1,0,0] op_sel_hi:[0,1,0]
	v_sub_f32_e32 v34, v52, v54
	v_sub_f32_e32 v30, v42, v56
	v_mov_b32_e32 v42, v44
	v_mov_b32_e32 v43, v46
	v_mov_b32_e32 v36, v48
	v_mov_b32_e32 v37, v50
.LBB0_739:
	v_cvt_pk_bf16_f32 v44, v34, v35
	v_cvt_pk_bf16_f32 v45, v42, v43
	v_cvt_pk_bf16_f32 v46, v30, v31
	v_mov_b64_e32 v[30:31], s[16:17]
	v_mad_i64_i32 v[30:31], s[2:3], v38, s75, v[30:31]
	v_mov_b32_e32 v41, v40
	v_cvt_pk_bf16_f32 v47, v36, v37
	v_lshl_add_u64 v[34:35], v[128:129], 1, v[30:31]
	v_mov_b32_e32 v36, v40
	v_mov_b32_e32 v37, v40
	global_store_dwordx4 v[34:35], v[44:47], off nt
	v_pk_mul_f32 v[34:35], v[28:29], v[36:37]
	v_pk_mul_f32 v[26:27], v[26:27], v[40:41]
	v_pk_mul_f32 v[28:29], v[24:25], v[36:37]
	s_and_b64 vcc, exec, s[10:11]
	v_pk_mul_f32 v[22:23], v[22:23], v[40:41]
	s_cbranch_vccnz .LBB0_741
	v_mov_b32_e32 v127, v1
	v_lshl_add_u64 v[24:25], v[32:33], 0, v[126:127]
	global_load_dwordx4 v[36:39], v[24:25], off
	global_load_dwordx4 v[40:43], v[24:25], off offset:16
	s_waitcnt vmcnt(0) lgkmcnt(0)
	v_pk_mul_f32 v[32:33], v[26:27], v[36:37] op_sel:[1,1] op_sel_hi:[0,1]
	v_mul_f32_e32 v0, v35, v39
	v_pk_mul_f32 v[24:25], v[26:27], v[36:37]
	v_pk_fma_f32 v[26:27], v[26:27], v[36:37], v[32:33] op_sel_hi:[1,0,1]
	v_pk_fma_f32 v[36:37], v[34:35], v[38:39], v[0:1] op_sel_hi:[1,1,0] neg_lo:[0,0,1] neg_hi:[0,0,1]
	v_mul_f32_e32 v0, v34, v39
	v_pk_fma_f32 v[38:39], v[34:35], v[38:39], v[0:1] op_sel:[1,0,0] op_sel_hi:[0,1,0]
	v_pk_mul_f32 v[44:45], v[22:23], v[40:41] op_sel:[1,1] op_sel_hi:[0,1]
	v_mul_f32_e32 v0, v29, v43
	v_pk_mul_f32 v[34:35], v[22:23], v[40:41]
	v_pk_fma_f32 v[22:23], v[22:23], v[40:41], v[44:45] op_sel_hi:[1,0,1]
	v_pk_fma_f32 v[40:41], v[28:29], v[42:43], v[0:1] op_sel_hi:[1,1,0] neg_lo:[0,0,1] neg_hi:[0,0,1]
	v_mul_f32_e32 v0, v28, v43
	v_pk_fma_f32 v[42:43], v[28:29], v[42:43], v[0:1] op_sel:[1,0,0] op_sel_hi:[0,1,0]
	v_sub_f32_e32 v26, v24, v32
	v_sub_f32_e32 v22, v34, v44
	v_mov_b32_e32 v34, v36
	v_mov_b32_e32 v35, v38
	v_mov_b32_e32 v28, v40
	v_mov_b32_e32 v29, v42
; __device__ __forceinline__ unsigned cvt_pk_bf16(float lo, float hi) { unsigned r; asm volatile("v_cvt_pk_bf16_f32 %0, %1, %2" : "=v"(r) : "v"(lo), "v"(hi)); return r; }
; #define PG8_BAR __builtin_amdgcn_s_barrier()
; template <class Epi, class Sched, bool ALIGN_EPI = false, bool SP2 = false>
; __device__ __forceinline__ void gemm_phase(PG8_LAS unsigned char* lds, const Gemm g, const Sched& S, const Epi& E, const int wave_s) {
;     ...
;         cur = nxt; cA = nA; cB = nB; ++ui;
;         if constexpr (ALIGN_EPI) { if (wr == 1) PG8_BAR; }
;     __device__ __forceinline__ void operator()(const f32x4 (&acc)[2][2][4][2], const Unit& u, int wr, int wc, int fr, int fq) const {
;     ...
;             for (int m = 0; m < 4; ++m) {
;                 const int row = row0 + ai * HALF + m * 16;
;                 const float rs = rsv[ai * 4 + m];
; #pragma unroll
;                 for (int bj = 0; bj < 2; ++bj) {
;                     const int colw = u.pn * BM + bj * HALF + wc * 32, col0 = colw + 8 * fq;
;                     const bool rope = (colw % 96) == 64 && colw < 576;
;                     f32x4 v0 = acc[ai][bj][m][0] * rs, v1 = acc[ai][bj][m][1] * rs;
;                     if (rope) {
;                         const float* tp = ropB + ((size_t)row * 16 + ((col0 - colw) >> 1)) * 2;
;                         const f32x4 c0 = *(const f32x4*)tp, c1 = *(const f32x4*)(tp + 4);
;                         f32x4 w0, w1;
;                         w0[0] = v0[0] * c0[0] - v0[1] * c0[1]; w0[1] = v0[1] * c0[0] + v0[0] * c0[1];
;                         w0[2] = v0[2] * c0[2] - v0[3] * c0[3]; w0[3] = v0[3] * c0[2] + v0[2] * c0[3];
;                         w1[0] = v1[0] * c1[0] - v1[1] * c1[1]; w1[1] = v1[1] * c1[0] + v1[0] * c1[1];
;                         w1[2] = v1[2] * c1[2] - v1[3] * c1[3]; w1[3] = v1[3] * c1[2] + v1[2] * c1[3];
;                         v0 = w0; v1 = w1;
;                     }
;                     u32x4 w; w.x = cvt_pk_bf16(v0[0], v0[1]); w.y = cvt_pk_bf16(v0[2], v0[3]); w.z = cvt_pk_bf16(v1[0], v1[1]); w.w = cvt_pk_bf16(v1[2], v1[3]);
;                     *(u32x4*)(O + (size_t)row * QMP + col0) = w;
;                 }
.LBB0_741:
	v_ffbh_u32_e32 v0, v143
	v_min_u32_e32 v0, 32, v0
	v_lshlrev_b64 v[24:25], v0, v[142:143]
	v_min_u32_e32 v24, 1, v24
	v_or_b32_e32 v24, v25, v24
	v_cvt_f32_u32_e32 v24, v24
	v_sub_u32_e32 v0, 32, v0
	v_ldexp_f32 v0, v24, v0
	v_mul_f32_e32 v0, 0x33800000, v0
	v_fmamk_f32 v0, v0, 0x3b2aaaab, v226
	v_cvt_pk_bf16_f32 v32, v26, v27
	v_cvt_pk_bf16_f32 v33, v34, v35
	v_cvt_pk_bf16_f32 v34, v22, v23
	v_lshl_add_u64 v[22:23], v[118:119], 1, v[30:31]
	v_cvt_pk_bf16_f32 v35, v28, v29
	global_store_dwordx4 v[22:23], v[32:35], off offset:256 nt
	v_add_u32_e32 v22, 0xb0, v140
	v_ashrrev_i32_e32 v23, 31, v22
	v_rsq_f32_e32 v24, v0
	s_nop 0
	v_mul_f32_e32 v24, s69, v24
	v_lshlrev_b64 v[28:29], 7, v[22:23]
	v_pk_mul_f32 v[26:27], v[20:21], v[24:25] op_sel_hi:[1,0]
	v_pk_mul_f32 v[18:19], v[18:19], v[24:25] op_sel_hi:[1,0]
	v_pk_mul_f32 v[20:21], v[12:13], v[24:25] op_sel_hi:[1,0]
	v_pk_mul_f32 v[12:13], v[10:11], v[24:25] op_sel_hi:[1,0]
	s_and_b64 vcc, exec, s[8:9]
	v_lshl_add_u64 v[10:11], s[20:21], 0, v[28:29]
	s_cbranch_vccnz .LBB0_743
	v_mov_b32_e32 v127, v1
	v_lshl_add_u64 v[32:33], v[10:11], 0, v[126:127]
	global_load_dwordx4 v[28:31], v[32:33], off
	s_nop 0
	global_load_dwordx4 v[32:35], v[32:33], off offset:16
	s_waitcnt vmcnt(0) lgkmcnt(0)
	v_pk_mul_f32 v[38:39], v[18:19], v[28:29] op_sel:[1,1] op_sel_hi:[0,1]
	v_mul_f32_e32 v0, v27, v31
	v_pk_mul_f32 v[36:37], v[18:19], v[28:29]
	v_pk_fma_f32 v[18:19], v[18:19], v[28:29], v[38:39] op_sel_hi:[1,0,1]
	v_pk_fma_f32 v[28:29], v[26:27], v[30:31], v[0:1] op_sel_hi:[1,1,0] neg_lo:[0,0,1] neg_hi:[0,0,1]
	v_mul_f32_e32 v0, v26, v31
	v_pk_fma_f32 v[30:31], v[26:27], v[30:31], v[0:1] op_sel:[1,0,0] op_sel_hi:[0,1,0]
	v_pk_mul_f32 v[40:41], v[12:13], v[32:33] op_sel:[1,1] op_sel_hi:[0,1]
	v_mul_f32_e32 v0, v21, v35
	v_pk_mul_f32 v[26:27], v[12:13], v[32:33]
	v_pk_fma_f32 v[12:13], v[12:13], v[32:33], v[40:41] op_sel_hi:[1,0,1]
	v_pk_fma_f32 v[32:33], v[20:21], v[34:35], v[0:1] op_sel_hi:[1,1,0] neg_lo:[0,0,1] neg_hi:[0,0,1]
	v_mul_f32_e32 v0, v20, v35
	v_pk_fma_f32 v[34:35], v[20:21], v[34:35], v[0:1] op_sel:[1,0,0] op_sel_hi:[0,1,0]
	v_sub_f32_e32 v18, v36, v38
	v_sub_f32_e32 v12, v26, v40
	v_mov_b32_e32 v26, v28
	v_mov_b32_e32 v27, v30
	v_mov_b32_e32 v20, v32
	v_mov_b32_e32 v21, v34
.LBB0_743:
	v_cvt_pk_bf16_f32 v28, v18, v19
	v_cvt_pk_bf16_f32 v29, v26, v27
	v_cvt_pk_bf16_f32 v30, v12, v13
	v_mov_b64_e32 v[12:13], s[16:17]
	v_mad_i64_i32 v[12:13], s[2:3], v22, s75, v[12:13]
	v_lshl_add_u64 v[18:19], v[128:129], 1, v[12:13]
	v_mov_b32_e32 v25, v24
	v_cvt_pk_bf16_f32 v31, v20, v21
	global_store_dwordx4 v[18:19], v[28:31], off nt
	v_mov_b32_e32 v18, v24
	v_mov_b32_e32 v19, v24
	v_pk_mul_f32 v[8:9], v[8:9], v[18:19]
	v_pk_mul_f32 v[6:7], v[6:7], v[24:25]
	v_pk_mul_f32 v[4:5], v[4:5], v[18:19]
	s_and_b64 vcc, exec, s[10:11]
	v_pk_mul_f32 v[2:3], v[2:3], v[24:25]
	s_cbranch_vccnz .LBB0_745
	v_mov_b32_e32 v127, v1
	v_lshl_add_u64 v[10:11], v[10:11], 0, v[126:127]
	global_load_dwordx4 v[18:21], v[10:11], off
	global_load_dwordx4 v[22:25], v[10:11], off offset:16
	s_waitcnt vmcnt(0) lgkmcnt(0)
	v_pk_mul_f32 v[26:27], v[6:7], v[18:19] op_sel:[1,1] op_sel_hi:[0,1]
	v_mul_f32_e32 v0, v9, v21
	v_pk_mul_f32 v[10:11], v[6:7], v[18:19]
	v_pk_fma_f32 v[6:7], v[6:7], v[18:19], v[26:27] op_sel_hi:[1,0,1]
	v_pk_fma_f32 v[18:19], v[8:9], v[20:21], v[0:1] op_sel_hi:[1,1,0] neg_lo:[0,0,1] neg_hi:[0,0,1]
	v_mul_f32_e32 v0, v8, v21
	v_pk_fma_f32 v[20:21], v[8:9], v[20:21], v[0:1] op_sel:[1,0,0] op_sel_hi:[0,1,0]
	v_pk_mul_f32 v[28:29], v[2:3], v[22:23] op_sel:[1,1] op_sel_hi:[0,1]
	v_mul_f32_e32 v0, v5, v25
	v_pk_mul_f32 v[8:9], v[2:3], v[22:23]
	v_pk_fma_f32 v[2:3], v[2:3], v[22:23], v[28:29] op_sel_hi:[1,0,1]
	v_pk_fma_f32 v[22:23], v[4:5], v[24:25], v[0:1] op_sel_hi:[1,1,0] neg_lo:[0,0,1] neg_hi:[0,0,1]
	v_mul_f32_e32 v0, v4, v25
	v_pk_fma_f32 v[24:25], v[4:5], v[24:25], v[0:1] op_sel:[1,0,0] op_sel_hi:[0,1,0]
	v_sub_f32_e32 v6, v10, v26
	v_sub_f32_e32 v2, v8, v28
	v_mov_b32_e32 v8, v18
	v_mov_b32_e32 v9, v20
	v_mov_b32_e32 v4, v22
	v_mov_b32_e32 v5, v24
.LBB0_745:
	v_cvt_pk_bf16_f32 v6, v6, v7
	v_cvt_pk_bf16_f32 v7, v8, v9
	v_cvt_pk_bf16_f32 v8, v2, v3
	v_lshl_add_u64 v[2:3], v[118:119], 1, v[12:13]
	s_and_b64 vcc, exec, s[6:7]
	s_mov_b64 s[2:3], -1
	v_cvt_pk_bf16_f32 v9, v4, v5
	global_store_dwordx4 v[2:3], v[6:9], off offset:256 nt
	s_cbranch_vccnz .LBB0_704
	s_andn2_b64 vcc, exec, s[14:15]
	s_cbranch_vccnz .LBB0_703
	s_barrier
	s_branch .LBB0_703

; __device__ __forceinline__ unsigned cvt_pk_bf16(float lo, float hi) { unsigned r; asm volatile("v_cvt_pk_bf16_f32 %0, %1, %2" : "=v"(r) : "v"(lo), "v"(hi)); return r; }
; __device__ __forceinline__ float ssq_val(ssq_t v) { return (float)v * SSQ_IFX; }
;     __device__ __forceinline__ void operator()(const f32x4 (&acc)[2][2][4][2], const Unit& u, int wr, int wc, int fr, int fq) const {
;         const int row0 = u.pm * BM + wr * 64 + fr;
;         ssq_t sv[8]; float rsv[8];
; #pragma unroll
;         for (int i = 0; i < 8; ++i) sv[i] = ssq[row0 + (i >> 2) * HALF + (i & 3) * 16];
; #pragma unroll
;         for (int i = 0; i < 8; ++i) rsv[i] = 1.0f / sqrtf(ssq_val(sv[i]) * (1.0f / 256.0f) + EPS);
; #pragma unroll
;         for (int ai = 0; ai < 2; ++ai)
; #pragma unroll
;             for (int m = 0; m < 4; ++m) {
;                 const int row = row0 + ai * HALF + m * 16;
;                 const float rs = rsv[ai * 4 + m];
; #pragma unroll
;                 for (int bj = 0; bj < 2; ++bj) {
;                     const int col0 = u.pn * BM + bj * HALF + wc * 32 + 8 * fq;
;                     const f32x4 v0 = acc[ai][bj][m][0] * rs, v1 = acc[ai][bj][m][1] * rs;
;                     u32x4 w; w.x = cvt_pk_bf16(v0[0], v0[1]); w.y = cvt_pk_bf16(v0[2], v0[3]); w.z = cvt_pk_bf16(v1[0], v1[1]); w.w = cvt_pk_bf16(v1[2], v1[3]);
;                     *(u32x4*)(O + (size_t)row * KVP + col0) = w;
;                 }
.LBB0_761:
	s_lshl_b32 s3, s3, 8
	s_add_i32 s3, s3, s4
	v_mbcnt_lo_u32_b32 v145, -1, 0
	v_mbcnt_hi_u32_b32 v145, -1, v145
	v_mov_b32_e32 v226, 0x358637bd
	v_and_or_b32 v138, v145, 15, s3
	v_ashrrev_i32_e32 v139, 31, v138
	v_lshl_add_u64 v[142:143], v[138:139], 3, s[14:15]
	global_load_dwordx2 v[156:157], v[142:143], off
	global_load_dwordx2 v[158:159], v[142:143], off offset:128
	global_load_dwordx2 v[154:155], v[142:143], off offset:256
	global_load_dwordx2 v[152:153], v[142:143], off offset:384
	v_mov_b32_e32 v223, 0x260
	global_load_dwordx2 v[150:151], v[142:143], off offset:1024
	global_load_dwordx2 v[148:149], v[142:143], off offset:1152
	global_load_dwordx2 v[146:147], v[142:143], off offset:1280
	s_nop 0
	global_load_dwordx2 v[142:143], v[142:143], off offset:1408
	s_lshl_b32 s2, s2, 8
	v_add_u32_e32 v139, 0x80, v138
	v_mov_b32_e32 v222, v224
	v_mov_b64_e32 v[252:253], 0x300
	s_waitcnt vmcnt(0) lgkmcnt(0)
	v_ffbh_u32_e32 v140, v157
	v_min_u32_e32 v140, 32, v140
	v_lshlrev_b64 v[156:157], v140, v[156:157]
	v_min_u32_e32 v144, 1, v156
	v_or_b32_e32 v144, v157, v144
	v_cvt_f32_u32_e32 v144, v144
	v_sub_u32_e32 v140, 32, v140
	v_ldexp_f32 v140, v144, v140
	v_mul_f32_e32 v140, 0x33800000, v140
	v_fmamk_f32 v140, v140, 0x3b800000, v226
	v_rsq_f32_e32 v140, v140
	s_nop 0
	v_ffbh_u32_e32 v144, v159
	v_min_u32_e32 v144, 32, v144
	v_lshlrev_b64 v[156:157], v144, v[158:159]
	v_min_u32_e32 v156, 1, v156
	v_or_b32_e32 v156, v157, v156
	v_cvt_f32_u32_e32 v156, v156
	v_sub_u32_e32 v144, 32, v144
	v_pk_mul_f32 v[132:133], v[132:133], v[140:141] op_sel_hi:[1,0]
	v_pk_mul_f32 v[130:131], v[130:131], v[140:141] op_sel_hi:[1,0]
	v_ldexp_f32 v144, v156, v144
	v_mul_f32_e32 v144, 0x33800000, v144
	v_fmamk_f32 v144, v144, 0x3b800000, v226
	v_pk_mul_f32 v[126:127], v[126:127], v[140:141] op_sel_hi:[1,0]
	v_pk_mul_f32 v[128:129], v[128:129], v[140:141] op_sel_hi:[1,0]
	v_cvt_pk_bf16_f32 v130, v130, v131
	v_cvt_pk_bf16_f32 v131, v132, v133
	v_cvt_pk_bf16_f32 v132, v126, v127
	v_mov_b64_e32 v[126:127], s[12:13]
	v_cvt_pk_bf16_f32 v133, v128, v129
	v_pk_mul_f32 v[124:125], v[124:125], v[140:141] op_sel_hi:[1,0]
	v_pk_mul_f32 v[122:123], v[122:123], v[140:141] op_sel_hi:[1,0]
	v_rsq_f32_e32 v144, v144
	s_nop 0
	v_ffbh_u32_e32 v156, v155
	v_min_u32_e32 v156, 32, v156
	v_lshlrev_b64 v[154:155], v156, v[154:155]
	v_min_u32_e32 v154, 1, v154
	v_or_b32_e32 v154, v155, v154
	v_cvt_f32_u32_e32 v154, v154
	v_sub_u32_e32 v155, 32, v156
	v_pk_mul_f32 v[114:115], v[114:115], v[144:145] op_sel_hi:[1,0]
	v_pk_mul_f32 v[116:117], v[116:117], v[144:145] op_sel_hi:[1,0]
	v_ldexp_f32 v154, v154, v155
	v_mul_f32_e32 v154, 0x33800000, v154
	v_fmamk_f32 v154, v154, 0x3b800000, v226
	v_pk_mul_f32 v[108:109], v[108:109], v[144:145] op_sel_hi:[1,0]
	v_pk_mul_f32 v[106:107], v[106:107], v[144:145] op_sel_hi:[1,0]
	v_rsq_f32_e32 v154, v154
	s_nop 0
	v_ffbh_u32_e32 v155, v153
	v_min_u32_e32 v155, 32, v155
	v_lshlrev_b64 v[152:153], v155, v[152:153]
	v_min_u32_e32 v152, 1, v152
	v_or_b32_e32 v152, v153, v152
	v_cvt_f32_u32_e32 v152, v152
	v_sub_u32_e32 v153, 32, v155
	v_ldexp_f32 v152, v152, v153
	v_mul_f32_e32 v152, 0x33800000, v152
	v_fmamk_f32 v152, v152, 0x3b800000, v226
	v_rsq_f32_e32 v152, v152
	s_nop 0
	v_ffbh_u32_e32 v153, v151
	v_min_u32_e32 v153, 32, v153
	v_lshlrev_b64 v[150:151], v153, v[150:151]
	v_min_u32_e32 v150, 1, v150
	v_or_b32_e32 v150, v151, v150
	v_cvt_f32_u32_e32 v150, v150
	v_sub_u32_e32 v151, 32, v153
	v_ldexp_f32 v150, v150, v151
	v_mul_f32_e32 v150, 0x33800000, v150
	v_fmamk_f32 v150, v150, 0x3b800000, v226
	v_rsq_f32_e32 v150, v150
	s_nop 0
	v_ffbh_u32_e32 v151, v149
	v_min_u32_e32 v151, 32, v151
	v_lshlrev_b64 v[148:149], v151, v[148:149]
	v_min_u32_e32 v148, 1, v148
	v_or_b32_e32 v148, v149, v148
	v_cvt_f32_u32_e32 v148, v148
	v_sub_u32_e32 v149, 32, v151
	v_ldexp_f32 v148, v148, v149
	v_mul_f32_e32 v148, 0x33800000, v148
	v_fmamk_f32 v148, v148, 0x3b800000, v226
	v_rsq_f32_e32 v148, v148
	s_nop 0
	v_ffbh_u32_e32 v149, v147
	v_min_u32_e32 v149, 32, v149
	v_lshlrev_b64 v[146:147], v149, v[146:147]
	v_min_u32_e32 v146, 1, v146
	v_or_b32_e32 v146, v147, v146
	v_cvt_f32_u32_e32 v146, v146
	v_sub_u32_e32 v147, 32, v149
	v_ldexp_f32 v146, v146, v147
	v_mul_f32_e32 v146, 0x33800000, v146
	v_fmamk_f32 v146, v146, 0x3b800000, v226
	v_rsq_f32_e32 v146, v146
	s_nop 0
	v_ffbh_u32_e32 v147, v143
	v_min_u32_e32 v147, 32, v147
	v_lshlrev_b64 v[142:143], v147, v[142:143]
	v_min_u32_e32 v142, 1, v142
	v_or_b32_e32 v142, v143, v142
	v_cvt_f32_u32_e32 v142, v142
	v_sub_u32_e32 v143, 32, v147
	v_pk_mul_f32 v[98:99], v[98:99], v[154:155] op_sel_hi:[1,0]
	v_pk_mul_f32 v[100:101], v[100:101], v[154:155] op_sel_hi:[1,0]
	v_ldexp_f32 v142, v142, v143
	v_mul_f32_e32 v142, 0x33800000, v142
	v_fmamk_f32 v142, v142, 0x3b800000, v226
	v_pk_mul_f32 v[92:93], v[92:93], v[154:155] op_sel_hi:[1,0]
	v_pk_mul_f32 v[90:91], v[90:91], v[154:155] op_sel_hi:[1,0]
	v_rsq_f32_e32 v142, v142
	s_nop 0
	v_lshrrev_b32_e32 v143, 1, v145
	v_and_or_b32 v143, v143, 24, s2
	v_or_b32_e32 v156, s5, v143
	v_ashrrev_i32_e32 v157, 31, v156
	v_mad_i64_i32 v[158:159], s[2:3], v138, s75, v[126:127]
	v_lshlrev_b64 v[128:129], 1, v[156:157]
	v_lshl_add_u64 v[156:157], v[158:159], 0, v[128:129]
	global_store_dwordx4 v[156:157], v[130:133], off nt
	v_pk_mul_f32 v[74:75], v[74:75], v[152:153] op_sel_hi:[1,0]
	v_pk_mul_f32 v[76:77], v[76:77], v[152:153] op_sel_hi:[1,0]
	v_pk_mul_f32 v[130:131], v[120:121], v[140:141] op_sel_hi:[1,0]
	v_pk_mul_f32 v[120:121], v[118:119], v[140:141] op_sel_hi:[1,0]
	v_cvt_pk_bf16_f32 v118, v122, v123
	v_cvt_pk_bf16_f32 v119, v124, v125
	v_pk_mul_f32 v[60:61], v[60:61], v[152:153] op_sel_hi:[1,0]
; __device__ __forceinline__ unsigned cvt_pk_bf16(float lo, float hi) { unsigned r; asm volatile("v_cvt_pk_bf16_f32 %0, %1, %2" : "=v"(r) : "v"(lo), "v"(hi)); return r; }
;     __device__ __forceinline__ void operator()(const f32x4 (&acc)[2][2][4][2], const Unit& u, int wr, int wc, int fr, int fq) const {
;     ...
; #pragma unroll
;                 for (int bj = 0; bj < 2; ++bj) {
;                     const int col0 = u.pn * BM + bj * HALF + wc * 32 + 8 * fq;
;                     const f32x4 v0 = acc[ai][bj][m][0] * rs, v1 = acc[ai][bj][m][1] * rs;
;                     u32x4 w; w.x = cvt_pk_bf16(v0[0], v0[1]); w.y = cvt_pk_bf16(v0[2], v0[3]); w.z = cvt_pk_bf16(v1[0], v1[1]); w.w = cvt_pk_bf16(v1[2], v1[3]);
;                     *(u32x4*)(O + (size_t)row * KVP + col0) = w;
;                 }
	v_cvt_pk_bf16_f32 v120, v120, v121
	v_cvt_pk_bf16_f32 v121, v130, v131
	global_store_dwordx4 v[156:157], v[118:121], off offset:256 nt
	v_pk_mul_f32 v[58:59], v[58:59], v[152:153] op_sel_hi:[1,0]
	v_pk_mul_f32 v[62:63], v[62:63], v[150:151] op_sel_hi:[1,0]
	v_or_b32_e32 v120, 16, v138
	v_pk_mul_f32 v[118:119], v[112:113], v[144:145] op_sel_hi:[1,0]
	v_pk_mul_f32 v[112:113], v[110:111], v[144:145] op_sel_hi:[1,0]
	v_cvt_pk_bf16_f32 v110, v114, v115
	v_mad_i64_i32 v[114:115], s[2:3], v120, s75, v[126:127]
	v_cvt_pk_bf16_f32 v111, v116, v117
	v_lshl_add_u64 v[114:115], v[114:115], 0, v[128:129]
	v_cvt_pk_bf16_f32 v112, v112, v113
	v_cvt_pk_bf16_f32 v113, v118, v119
	global_store_dwordx4 v[114:115], v[110:113], off nt
	v_pk_mul_f32 v[50:51], v[50:51], v[148:149] op_sel_hi:[1,0]
	v_pk_mul_f32 v[52:53], v[52:53], v[148:149] op_sel_hi:[1,0]
	v_pk_mul_f32 v[110:111], v[104:105], v[144:145] op_sel_hi:[1,0]
	v_pk_mul_f32 v[104:105], v[102:103], v[144:145] op_sel_hi:[1,0]
	v_cvt_pk_bf16_f32 v102, v106, v107
	v_cvt_pk_bf16_f32 v103, v108, v109
	v_pk_mul_f32 v[44:45], v[44:45], v[148:149] op_sel_hi:[1,0]
	v_cvt_pk_bf16_f32 v104, v104, v105
	v_cvt_pk_bf16_f32 v105, v110, v111
	global_store_dwordx4 v[114:115], v[102:105], off offset:256 nt
	v_pk_mul_f32 v[42:43], v[42:43], v[148:149] op_sel_hi:[1,0]
	v_pk_mul_f32 v[34:35], v[34:35], v[146:147] op_sel_hi:[1,0]
	v_or_b32_e32 v104, 32, v138
	v_pk_mul_f32 v[102:103], v[96:97], v[154:155] op_sel_hi:[1,0]
	v_pk_mul_f32 v[96:97], v[94:95], v[154:155] op_sel_hi:[1,0]
	v_cvt_pk_bf16_f32 v94, v98, v99
	v_mad_i64_i32 v[98:99], s[2:3], v104, s75, v[126:127]
	v_cvt_pk_bf16_f32 v95, v100, v101
	v_lshl_add_u64 v[98:99], v[98:99], 0, v[128:129]
	v_cvt_pk_bf16_f32 v96, v96, v97
	v_cvt_pk_bf16_f32 v97, v102, v103
	global_store_dwordx4 v[98:99], v[94:97], off nt
	v_pk_mul_f32 v[36:37], v[36:37], v[146:147] op_sel_hi:[1,0]
	v_pk_mul_f32 v[28:29], v[28:29], v[146:147] op_sel_hi:[1,0]
	v_pk_mul_f32 v[94:95], v[88:89], v[154:155] op_sel_hi:[1,0]
	v_pk_mul_f32 v[88:89], v[86:87], v[154:155] op_sel_hi:[1,0]
	v_cvt_pk_bf16_f32 v86, v90, v91
	v_cvt_pk_bf16_f32 v87, v92, v93
	v_pk_mul_f32 v[26:27], v[26:27], v[146:147] op_sel_hi:[1,0]
	v_cvt_pk_bf16_f32 v88, v88, v89
	v_cvt_pk_bf16_f32 v89, v94, v95
	global_store_dwordx4 v[98:99], v[86:89], off offset:256 nt
	v_pk_mul_f32 v[18:19], v[18:19], v[142:143] op_sel_hi:[1,0]
	v_pk_mul_f32 v[20:21], v[20:21], v[142:143] op_sel_hi:[1,0]
	v_or_b32_e32 v88, 48, v138
	v_pk_mul_f32 v[86:87], v[68:69], v[152:153] op_sel_hi:[1,0]
	v_pk_mul_f32 v[68:69], v[66:67], v[152:153] op_sel_hi:[1,0]
	v_cvt_pk_bf16_f32 v66, v74, v75
	v_mad_i64_i32 v[74:75], s[2:3], v88, s75, v[126:127]
	v_cvt_pk_bf16_f32 v67, v76, v77
	v_lshl_add_u64 v[74:75], v[74:75], 0, v[128:129]
	v_cvt_pk_bf16_f32 v68, v68, v69
	v_cvt_pk_bf16_f32 v69, v86, v87
	global_store_dwordx4 v[74:75], v[66:69], off nt
	s_and_b64 vcc, exec, s[6:7]
	v_pk_mul_f32 v[8:9], v[8:9], v[142:143] op_sel_hi:[1,0]
	v_pk_mul_f32 v[66:67], v[56:57], v[152:153] op_sel_hi:[1,0]
	v_pk_mul_f32 v[56:57], v[54:55], v[152:153] op_sel_hi:[1,0]
	v_cvt_pk_bf16_f32 v54, v58, v59
	v_cvt_pk_bf16_f32 v55, v60, v61
	v_pk_mul_f32 v[58:59], v[80:81], v[150:151] op_sel_hi:[1,0]
	v_cvt_pk_bf16_f32 v56, v56, v57
	v_cvt_pk_bf16_f32 v57, v66, v67
	global_store_dwordx4 v[74:75], v[54:57], off offset:256 nt
	v_pk_mul_f32 v[60:61], v[78:79], v[150:151] op_sel_hi:[1,0]
	v_pk_mul_f32 v[6:7], v[6:7], v[142:143] op_sel_hi:[1,0]
	v_pk_mul_f32 v[56:57], v[84:85], v[150:151] op_sel_hi:[1,0]
	v_pk_mul_f32 v[54:55], v[82:83], v[150:151] op_sel_hi:[1,0]
	s_nop 0
	v_cvt_pk_bf16_f32 v54, v54, v55
	v_cvt_pk_bf16_f32 v55, v56, v57
	v_cvt_pk_bf16_f32 v56, v60, v61
	v_cvt_pk_bf16_f32 v57, v58, v59
	v_mad_i64_i32 v[58:59], s[2:3], v139, s75, v[126:127]
	v_lshl_add_u64 v[58:59], v[58:59], 0, v[128:129]
	global_store_dwordx4 v[58:59], v[54:57], off nt
	v_pk_mul_f32 v[60:61], v[64:65], v[150:151] op_sel_hi:[1,0]
	s_nop 0
	v_pk_mul_f32 v[56:57], v[72:73], v[150:151] op_sel_hi:[1,0]
	v_pk_mul_f32 v[54:55], v[70:71], v[150:151] op_sel_hi:[1,0]
	s_nop 0
	v_cvt_pk_bf16_f32 v54, v54, v55
	v_cvt_pk_bf16_f32 v55, v56, v57
	v_cvt_pk_bf16_f32 v56, v62, v63
	v_cvt_pk_bf16_f32 v57, v60, v61
	global_store_dwordx4 v[58:59], v[54:57], off offset:256 nt
	s_nop 1
	v_add_u32_e32 v56, 0x90, v138
	v_pk_mul_f32 v[54:55], v[48:49], v[148:149] op_sel_hi:[1,0]
	v_pk_mul_f32 v[48:49], v[46:47], v[148:149] op_sel_hi:[1,0]
	v_cvt_pk_bf16_f32 v46, v50, v51
	v_mad_i64_i32 v[50:51], s[2:3], v56, s75, v[126:127]
	v_cvt_pk_bf16_f32 v47, v52, v53
	v_lshl_add_u64 v[50:51], v[50:51], 0, v[128:129]
	v_cvt_pk_bf16_f32 v48, v48, v49
	v_cvt_pk_bf16_f32 v49, v54, v55
	global_store_dwordx4 v[50:51], v[46:49], off nt
	s_nop 1
	v_pk_mul_f32 v[46:47], v[40:41], v[148:149] op_sel_hi:[1,0]
	v_pk_mul_f32 v[40:41], v[38:39], v[148:149] op_sel_hi:[1,0]
	v_cvt_pk_bf16_f32 v38, v42, v43
	v_cvt_pk_bf16_f32 v39, v44, v45
	s_nop 0
	v_cvt_pk_bf16_f32 v40, v40, v41
	v_cvt_pk_bf16_f32 v41, v46, v47
	global_store_dwordx4 v[50:51], v[38:41], off offset:256 nt
	s_nop 1
	v_add_u32_e32 v40, 0xa0, v138
	v_pk_mul_f32 v[38:39], v[32:33], v[146:147] op_sel_hi:[1,0]
	v_pk_mul_f32 v[32:33], v[30:31], v[146:147] op_sel_hi:[1,0]
	v_cvt_pk_bf16_f32 v30, v34, v35
	v_mad_i64_i32 v[34:35], s[2:3], v40, s75, v[126:127]
	v_cvt_pk_bf16_f32 v31, v36, v37
	v_lshl_add_u64 v[34:35], v[34:35], 0, v[128:129]
	v_cvt_pk_bf16_f32 v32, v32, v33
	v_cvt_pk_bf16_f32 v33, v38, v39
	global_store_dwordx4 v[34:35], v[30:33], off nt
	s_nop 1
	v_pk_mul_f32 v[30:31], v[24:25], v[146:147] op_sel_hi:[1,0]
	v_pk_mul_f32 v[24:25], v[22:23], v[146:147] op_sel_hi:[1,0]
	v_cvt_pk_bf16_f32 v22, v26, v27
	v_cvt_pk_bf16_f32 v23, v28, v29
	s_nop 0
	v_cvt_pk_bf16_f32 v24, v24, v25
	v_cvt_pk_bf16_f32 v25, v30, v31
	global_store_dwordx4 v[34:35], v[22:25], off offset:256 nt
	s_nop 1
	v_add_u32_e32 v24, 0xb0, v138
	v_pk_mul_f32 v[22:23], v[12:13], v[142:143] op_sel_hi:[1,0]
	v_pk_mul_f32 v[12:13], v[10:11], v[142:143] op_sel_hi:[1,0]
	v_cvt_pk_bf16_f32 v10, v18, v19
	v_mad_i64_i32 v[18:19], s[2:3], v24, s75, v[126:127]
	v_cvt_pk_bf16_f32 v11, v20, v21
	v_lshl_add_u64 v[18:19], v[18:19], 0, v[128:129]
	v_cvt_pk_bf16_f32 v12, v12, v13
	v_cvt_pk_bf16_f32 v13, v22, v23
	global_store_dwordx4 v[18:19], v[10:13], off nt
	s_mov_b64 s[2:3], -1
	s_nop 0
	v_pk_mul_f32 v[10:11], v[4:5], v[142:143] op_sel_hi:[1,0]
	v_pk_mul_f32 v[4:5], v[2:3], v[142:143] op_sel_hi:[1,0]
	v_cvt_pk_bf16_f32 v2, v6, v7
	v_cvt_pk_bf16_f32 v3, v8, v9
	s_nop 0
	v_cvt_pk_bf16_f32 v4, v4, v5
	v_cvt_pk_bf16_f32 v5, v10, v11
	global_store_dwordx4 v[18:19], v[2:5], off offset:256 nt
	s_cbranch_vccnz .LBB0_754
	s_andn2_b64 vcc, exec, s[10:11]
	s_cbranch_vccnz .LBB0_753
	s_barrier
	s_branch .LBB0_753

; #define PG8_LAS __attribute__((address_space(3)))
; __device__ __forceinline__ unsigned cvt_pk_bf16(float lo, float hi) { unsigned r; asm volatile("v_cvt_pk_bf16_f32 %0, %1, %2" : "=v"(r) : "v"(lo), "v"(hi)); return r; }
; __device__ __forceinline__ f32x2 swiglu_pk(f32x2 g, f32x2 u) {
;     const f32x2 t = g * (-LOG2E); f32x2 e; e.x = __builtin_amdgcn_exp2f(t.x); e.y = __builtin_amdgcn_exp2f(t.y);
;     const f32x2 d = e + 1.0f; f32x2 r; r.x = __builtin_amdgcn_rcpf(d.x); r.y = __builtin_amdgcn_rcpf(d.y);
;     return (g * r) * u;
; }
;     __device__ __forceinline__ void operator()(const f32x4 (&acc)[2][2][4][2], const Unit& u, int wr, int wc, int fr, int fq, int par, PG8_LAS unsigned char* lds) const {
;         const int row0 = u.pm * BM + wr * 64 + fr, col0 = u.pn * HALF + wc * 32 + 8 * fq;
;         const PG8_LAS float* rp = (const PG8_LAS float*)(lds + STAGE_BYTES + 5120) + par * 512;
;         const PG8_LAS float* sp = rp + 256 + wc * 32 + 8 * fq;
;         const f32x4 sg0 = *(const PG8_LAS f32x4*)sp, sg1 = *(const PG8_LAS f32x4*)(sp + 4), su0 = *(const PG8_LAS f32x4*)(sp + HALF), su1 = *(const PG8_LAS f32x4*)(sp + HALF + 4);
;         float rsv[8];
; #pragma unroll
;         for (int i = 0; i < 8; ++i) rsv[i] = rp[(i >> 2) * HALF + wr * 64 + (i & 3) * 16 + fr];
; #pragma unroll
;         for (int ai = 0; ai < 2; ++ai)
; #pragma unroll
;             for (int m = 0; m < 4; ++m) {
;                 const int row = row0 + ai * HALF + m * 16;
;                 const float rs = rsv[ai * 4 + m];
;                 const f32x4 g0 = acc[ai][0][m][0] * rs + sg0, g1 = acc[ai][0][m][1] * rs + sg1, u0 = acc[ai][1][m][0] * rs + su0, u1 = acc[ai][1][m][1] * rs + su1;
;                 f32x4 h0, h1;
;                 { const f32x2 a = swiglu_pk((f32x2){g0[0], g0[1]}, (f32x2){u0[0], u0[1]}), b2 = swiglu_pk((f32x2){g0[2], g0[3]}, (f32x2){u0[2], u0[3]});
;                   const f32x2 c = swiglu_pk((f32x2){g1[0], g1[1]}, (f32x2){u1[0], u1[1]}), d = swiglu_pk((f32x2){g1[2], g1[3]}, (f32x2){u1[2], u1[3]});
;                   h0 = (f32x4){a.x, a.y, b2.x, b2.y}; h1 = (f32x4){c.x, c.y, d.x, d.y}; }
;                 u32x4 w; w.x = cvt_pk_bf16(h0[0], h0[1]); w.y = cvt_pk_bf16(h0[2], h0[3]); w.z = cvt_pk_bf16(h1[0], h1[1]); w.w = cvt_pk_bf16(h1[2], h1[3]);
;                 *(gs_u32x4*)(PG8_GPTR(O) + (unsigned)(row * FFN + col0) * 2u) = w;
;             }
.LBB0_1174:
	s_lshl_b32 s2, s28, 8
	v_mbcnt_lo_u32_b32 v0, -1, 0
	v_mbcnt_hi_u32_b32 v0, -1, v0
	s_add_i32 s2, s2, s47
	v_and_b32_e32 v160, 15, v0
	v_or_b32_e32 v167, s2, v160
	s_lshl_b32 s2, s52, 11
	s_and_b32 s2, s2, 0x800
	s_add_i32 s2, s2, 0
	v_lshrrev_b32_e32 v0, 1, v0
	s_add_i32 s2, s2, 0x21400
	s_lshl_b32 s3, s48, 2
	v_and_b32_e32 v0, 24, v0
	s_add_i32 s3, s2, s3
	v_lshl_add_u32 v90, v0, 2, s3
	s_lshl_b32 s3, s47, 2
	s_add_i32 s2, s2, s3
	v_lshl_add_u32 v160, v160, 2, s2
	ds_read_b128 v[106:109], v90 offset:1024
	ds_read_b128 v[102:105], v90 offset:1040
	ds_read_b128 v[98:101], v90 offset:1536
	ds_read_b128 v[90:93], v90 offset:1552
	ds_read2_b32 v[168:169], v160 offset1:16
	ds_read2_b32 v[164:165], v160 offset0:32 offset1:48
	ds_read2_b32 v[162:163], v160 offset0:128 offset1:144
	ds_read2_b32 v[160:161], v160 offset0:160 offset1:176
	s_lshl_b32 s2, s26, 7
	s_waitcnt lgkmcnt(0)
	v_pk_fma_f32 v[146:147], v[146:147], v[168:169], v[106:107] op_sel_hi:[1,0,1]
	v_pk_fma_f32 v[148:149], v[148:149], v[168:169], v[108:109] op_sel_hi:[1,0,1]
	v_pk_mul_f32 v[170:171], v[146:147], s[84:85] op_sel_hi:[1,0]
	v_pk_fma_f32 v[138:139], v[138:139], v[168:169], v[98:99] op_sel_hi:[1,0,1]
	v_exp_f32_e32 v170, v170
	v_exp_f32_e32 v171, v171
	v_pk_fma_f32 v[142:143], v[142:143], v[168:169], v[102:103] op_sel_hi:[1,0,1]
	v_pk_fma_f32 v[140:141], v[140:141], v[168:169], v[100:101] op_sel_hi:[1,0,1]
	v_pk_fma_f32 v[144:145], v[144:145], v[168:169], v[104:105] op_sel_hi:[1,0,1]
	v_pk_add_f32 v[170:171], v[170:171], 1.0 op_sel_hi:[1,0]
	v_pk_fma_f32 v[134:135], v[134:135], v[168:169], v[90:91] op_sel_hi:[1,0,1]
	v_rcp_f32_e32 v170, v170
	v_rcp_f32_e32 v171, v171
	s_or_b32 s2, s2, s48
	v_or_b32_e32 v0, s2, v0
	v_pk_fma_f32 v[136:137], v[136:137], v[168:169], v[92:93] op_sel_hi:[1,0,1]
	v_pk_mul_f32 v[146:147], v[146:147], v[170:171]
	s_movk_i32 s2, 0xb00
	v_pk_mul_f32 v[138:139], v[138:139], v[146:147]
	v_pk_mul_f32 v[146:147], v[148:149], s[84:85] op_sel_hi:[1,0]
	v_pk_fma_f32 v[114:115], v[114:115], v[164:165], v[106:107] op_sel_hi:[1,0,1]
	v_exp_f32_e32 v146, v146
	v_exp_f32_e32 v147, v147
	v_pk_fma_f32 v[116:117], v[116:117], v[164:165], v[108:109] op_sel_hi:[1,0,1]
	v_pk_fma_f32 v[94:95], v[94:95], v[164:165], v[98:99] op_sel_hi:[1,0,1]
	v_pk_fma_f32 v[110:111], v[110:111], v[164:165], v[102:103] op_sel_hi:[1,0,1]
	v_pk_add_f32 v[146:147], v[146:147], 1.0 op_sel_hi:[1,0]
	v_pk_fma_f32 v[96:97], v[96:97], v[164:165], v[100:101] op_sel_hi:[1,0,1]
	v_rcp_f32_e32 v146, v146
	v_rcp_f32_e32 v147, v147
	v_pk_fma_f32 v[112:113], v[112:113], v[164:165], v[104:105] op_sel_hi:[1,0,1]
	v_pk_fma_f32 v[86:87], v[86:87], v[164:165], v[90:91] op_sel_hi:[1,0,1]
	v_pk_fma_f32 v[88:89], v[88:89], v[164:165], v[92:93] op_sel_hi:[1,0,1]
	v_pk_mul_f32 v[146:147], v[148:149], v[146:147]
	v_pk_fma_f32 v[66:67], v[66:67], v[162:163], v[106:107] op_sel_hi:[1,0,1]
	v_pk_mul_f32 v[140:141], v[140:141], v[146:147]
	v_pk_mul_f32 v[146:147], v[142:143], s[84:85] op_sel_hi:[1,0]
	v_pk_fma_f32 v[68:69], v[68:69], v[162:163], v[108:109] op_sel_hi:[1,0,1]
	v_exp_f32_e32 v146, v146
	v_exp_f32_e32 v147, v147
	v_pk_fma_f32 v[58:59], v[58:59], v[162:163], v[98:99] op_sel_hi:[1,0,1]
	v_pk_fma_f32 v[62:63], v[62:63], v[162:163], v[102:103] op_sel_hi:[1,0,1]
	v_pk_fma_f32 v[60:61], v[60:61], v[162:163], v[100:101] op_sel_hi:[1,0,1]
	v_pk_add_f32 v[146:147], v[146:147], 1.0 op_sel_hi:[1,0]
	v_pk_fma_f32 v[64:65], v[64:65], v[162:163], v[104:105] op_sel_hi:[1,0,1]
	v_rcp_f32_e32 v146, v146
	v_rcp_f32_e32 v147, v147
	v_pk_fma_f32 v[54:55], v[54:55], v[162:163], v[90:91] op_sel_hi:[1,0,1]
	v_pk_fma_f32 v[56:57], v[56:57], v[162:163], v[92:93] op_sel_hi:[1,0,1]
	v_pk_fma_f32 v[34:35], v[34:35], v[160:161], v[106:107] op_sel_hi:[1,0,1]
	v_pk_mul_f32 v[142:143], v[142:143], v[146:147]
	v_pk_fma_f32 v[36:37], v[36:37], v[160:161], v[108:109] op_sel_hi:[1,0,1]
	v_pk_mul_f32 v[142:143], v[134:135], v[142:143]
	v_pk_mul_f32 v[134:135], v[144:145], s[84:85] op_sel_hi:[1,0]
	v_pk_fma_f32 v[26:27], v[26:27], v[160:161], v[98:99] op_sel_hi:[1,0,1]
	v_exp_f32_e32 v134, v134
	v_exp_f32_e32 v135, v135
	v_pk_fma_f32 v[30:31], v[30:31], v[160:161], v[102:103] op_sel_hi:[1,0,1]
	v_pk_fma_f32 v[28:29], v[28:29], v[160:161], v[100:101] op_sel_hi:[1,0,1]
	v_pk_fma_f32 v[32:33], v[32:33], v[160:161], v[104:105] op_sel_hi:[1,0,1]
	v_pk_add_f32 v[134:135], v[134:135], 1.0 op_sel_hi:[1,0]
	v_pk_fma_f32 v[22:23], v[22:23], v[160:161], v[90:91] op_sel_hi:[1,0,1]
	v_rcp_f32_e32 v134, v134
	v_rcp_f32_e32 v135, v135
	v_pk_fma_f32 v[24:25], v[24:25], v[160:161], v[92:93] op_sel_hi:[1,0,1]
	s_and_b64 vcc, exec, s[6:7]
	v_pk_mul_f32 v[134:135], v[144:145], v[134:135]
	s_nop 0
	v_pk_mul_f32 v[144:145], v[136:137], v[134:135]
	v_cvt_pk_bf16_f32 v134, v138, v139
	v_mul_lo_u32 v138, v167, s2
	v_lshrrev_b32_e32 v245, 4, v167
	v_mul_u32_u24_e32 v245, 0x16000, v245
	v_and_b32_e32 v247, 15, v167
	v_lshl_add_u32 v245, v247, 6, v245
	v_lshrrev_b32_e32 v247, 5, v0
	v_lshl_add_u32 v245, v247, 10, v245
	v_and_b32_e32 v247, 31, v0
	v_lshl_add_u32 v245, v247, 1, v245
	v_add_lshl_u32 v0, v0, v138, 1
	v_mov_b32_e32 v0, v245
	v_cvt_pk_bf16_f32 v135, v140, v141
	v_cvt_pk_bf16_f32 v136, v142, v143
	v_cvt_pk_bf16_f32 v137, v144, v145
	global_store_dwordx4 v0, v[134:137], s[14:15] nt
	s_mov_b64 s[2:3], -1
	s_nop 0
	v_mov_b32_e32 v134, v169
	v_pk_fma_f32 v[130:131], v[130:131], v[134:135], v[106:107] op_sel_hi:[1,0,1]
	v_pk_fma_f32 v[132:133], v[132:133], v[134:135], v[108:109] op_sel_hi:[1,0,1]
	v_pk_fma_f32 v[128:129], v[128:129], v[134:135], v[104:105] op_sel_hi:[1,0,1]
	v_pk_fma_f32 v[126:127], v[126:127], v[134:135], v[102:103] op_sel_hi:[1,0,1]
; __device__ __forceinline__ unsigned cvt_pk_bf16(float lo, float hi) { unsigned r; asm volatile("v_cvt_pk_bf16_f32 %0, %1, %2" : "=v"(r) : "v"(lo), "v"(hi)); return r; }
; #define PG8_GPTR(p) ((__attribute__((address_space(1))) char*)(p))
; __device__ __forceinline__ f32x2 swiglu_pk(f32x2 g, f32x2 u) {
;     const f32x2 t = g * (-LOG2E); f32x2 e; e.x = __builtin_amdgcn_exp2f(t.x); e.y = __builtin_amdgcn_exp2f(t.y);
;     const f32x2 d = e + 1.0f; f32x2 r; r.x = __builtin_amdgcn_rcpf(d.x); r.y = __builtin_amdgcn_rcpf(d.y);
;     return (g * r) * u;
; }
;     __device__ __forceinline__ void operator()(const f32x4 (&acc)[2][2][4][2], const Unit& u, int wr, int wc, int fr, int fq, int par, PG8_LAS unsigned char* lds) const {
;     ...
;             for (int m = 0; m < 4; ++m) {
;                 const int row = row0 + ai * HALF + m * 16;
;                 const float rs = rsv[ai * 4 + m];
;                 const f32x4 g0 = acc[ai][0][m][0] * rs + sg0, g1 = acc[ai][0][m][1] * rs + sg1, u0 = acc[ai][1][m][0] * rs + su0, u1 = acc[ai][1][m][1] * rs + su1;
;                 f32x4 h0, h1;
;                 { const f32x2 a = swiglu_pk((f32x2){g0[0], g0[1]}, (f32x2){u0[0], u0[1]}), b2 = swiglu_pk((f32x2){g0[2], g0[3]}, (f32x2){u0[2], u0[3]});
;                   const f32x2 c = swiglu_pk((f32x2){g1[0], g1[1]}, (f32x2){u1[0], u1[1]}), d = swiglu_pk((f32x2){g1[2], g1[3]}, (f32x2){u1[2], u1[3]});
;                   h0 = (f32x4){a.x, a.y, b2.x, b2.y}; h1 = (f32x4){c.x, c.y, d.x, d.y}; }
;                 u32x4 w; w.x = cvt_pk_bf16(h0[0], h0[1]); w.y = cvt_pk_bf16(h0[2], h0[3]); w.z = cvt_pk_bf16(h1[0], h1[1]); w.w = cvt_pk_bf16(h1[2], h1[3]);
;                 *(gs_u32x4*)(PG8_GPTR(O) + (unsigned)(row * FFN + col0) * 2u) = w;
;             }
	v_pk_fma_f32 v[124:125], v[124:125], v[134:135], v[100:101] op_sel_hi:[1,0,1]
	v_pk_fma_f32 v[122:123], v[122:123], v[134:135], v[98:99] op_sel_hi:[1,0,1]
	v_pk_fma_f32 v[120:121], v[120:121], v[134:135], v[92:93] op_sel_hi:[1,0,1]
	v_pk_fma_f32 v[118:119], v[118:119], v[134:135], v[90:91] op_sel_hi:[1,0,1]
	v_pk_mul_f32 v[134:135], v[130:131], s[84:85] op_sel_hi:[1,0]
	s_nop 0
	v_exp_f32_e32 v134, v134
	v_exp_f32_e32 v135, v135
	s_nop 0
	v_pk_add_f32 v[134:135], v[134:135], 1.0 op_sel_hi:[1,0]
	s_nop 0
	v_rcp_f32_e32 v134, v134
	v_rcp_f32_e32 v135, v135
	s_nop 0
	v_pk_mul_f32 v[130:131], v[130:131], v[134:135]
	s_nop 0
	v_pk_mul_f32 v[122:123], v[122:123], v[130:131]
	v_pk_mul_f32 v[130:131], v[132:133], s[84:85] op_sel_hi:[1,0]
	s_nop 0
	v_exp_f32_e32 v130, v130
	v_exp_f32_e32 v131, v131
	s_nop 0
	v_pk_add_f32 v[130:131], v[130:131], 1.0 op_sel_hi:[1,0]
	s_nop 0
	v_rcp_f32_e32 v130, v130
	v_rcp_f32_e32 v131, v131
	s_nop 0
	v_pk_mul_f32 v[130:131], v[132:133], v[130:131]
	s_nop 0
	v_pk_mul_f32 v[124:125], v[124:125], v[130:131]
	v_pk_mul_f32 v[130:131], v[126:127], s[84:85] op_sel_hi:[1,0]
	s_nop 0
	v_exp_f32_e32 v130, v130
	v_exp_f32_e32 v131, v131
	s_nop 0
	v_pk_add_f32 v[130:131], v[130:131], 1.0 op_sel_hi:[1,0]
	s_nop 0
	v_rcp_f32_e32 v130, v130
	v_rcp_f32_e32 v131, v131
	s_nop 0
	v_pk_mul_f32 v[126:127], v[126:127], v[130:131]
	s_nop 0
	v_pk_mul_f32 v[126:127], v[118:119], v[126:127]
	v_pk_mul_f32 v[118:119], v[128:129], s[84:85] op_sel_hi:[1,0]
	s_nop 0
	v_exp_f32_e32 v118, v118
	v_exp_f32_e32 v119, v119
	s_nop 0
	v_pk_add_f32 v[118:119], v[118:119], 1.0 op_sel_hi:[1,0]
	s_nop 0
	v_rcp_f32_e32 v118, v118
	v_rcp_f32_e32 v119, v119
	s_nop 0
	v_pk_mul_f32 v[118:119], v[128:129], v[118:119]
	s_nop 0
	v_pk_mul_f32 v[128:129], v[120:121], v[118:119]
	v_cvt_pk_bf16_f32 v118, v122, v123
	v_cvt_pk_bf16_f32 v119, v124, v125
	v_add_u32_e32 v122, 0x16000, v0
	v_cvt_pk_bf16_f32 v120, v126, v127
	v_cvt_pk_bf16_f32 v121, v128, v129
	global_store_dwordx4 v122, v[118:121], s[14:15] nt
	s_nop 1
	v_pk_mul_f32 v[118:119], v[114:115], s[84:85] op_sel_hi:[1,0]
	s_nop 0
	v_exp_f32_e32 v118, v118
	v_exp_f32_e32 v119, v119
	s_nop 0
	v_pk_add_f32 v[118:119], v[118:119], 1.0 op_sel_hi:[1,0]
	s_nop 0
	v_rcp_f32_e32 v118, v118
	v_rcp_f32_e32 v119, v119
	s_nop 0
	v_pk_mul_f32 v[114:115], v[114:115], v[118:119]
	s_nop 0
	v_pk_mul_f32 v[94:95], v[94:95], v[114:115]
	v_pk_mul_f32 v[114:115], v[116:117], s[84:85] op_sel_hi:[1,0]
	s_nop 0
	v_exp_f32_e32 v114, v114
	v_exp_f32_e32 v115, v115
	s_nop 0
	v_pk_add_f32 v[114:115], v[114:115], 1.0 op_sel_hi:[1,0]
	s_nop 0
	v_rcp_f32_e32 v114, v114
	v_rcp_f32_e32 v115, v115
	s_nop 0
	v_pk_mul_f32 v[114:115], v[116:117], v[114:115]
	s_nop 0
	v_pk_mul_f32 v[96:97], v[96:97], v[114:115]
	v_pk_mul_f32 v[114:115], v[110:111], s[84:85] op_sel_hi:[1,0]
	s_nop 0
	v_exp_f32_e32 v114, v114
	v_exp_f32_e32 v115, v115
	s_nop 0
	v_pk_add_f32 v[114:115], v[114:115], 1.0 op_sel_hi:[1,0]
	s_nop 0
	v_rcp_f32_e32 v114, v114
	v_rcp_f32_e32 v115, v115
	s_nop 0
	v_pk_mul_f32 v[110:111], v[110:111], v[114:115]
	s_nop 0
	v_pk_mul_f32 v[110:111], v[86:87], v[110:111]
	v_pk_mul_f32 v[86:87], v[112:113], s[84:85] op_sel_hi:[1,0]
	s_nop 0
	v_exp_f32_e32 v86, v86
	v_exp_f32_e32 v87, v87
	s_nop 0
	v_pk_add_f32 v[86:87], v[86:87], 1.0 op_sel_hi:[1,0]
	s_nop 0
	v_rcp_f32_e32 v86, v86
	v_rcp_f32_e32 v87, v87
	s_nop 0
	v_pk_mul_f32 v[86:87], v[112:113], v[86:87]
	s_nop 0
	v_pk_mul_f32 v[112:113], v[88:89], v[86:87]
	v_cvt_pk_bf16_f32 v86, v94, v95
	v_add_u32_e32 v94, 0x2c000, v0
	v_cvt_pk_bf16_f32 v87, v96, v97
	v_cvt_pk_bf16_f32 v88, v110, v111
	v_cvt_pk_bf16_f32 v89, v112, v113
	global_store_dwordx4 v94, v[86:89], s[14:15] nt
	s_nop 1
	v_mov_b32_e32 v86, v165
	v_pk_fma_f32 v[82:83], v[82:83], v[86:87], v[106:107] op_sel_hi:[1,0,1]
	v_pk_fma_f32 v[84:85], v[84:85], v[86:87], v[108:109] op_sel_hi:[1,0,1]
	v_pk_fma_f32 v[80:81], v[80:81], v[86:87], v[104:105] op_sel_hi:[1,0,1]
	v_pk_fma_f32 v[78:79], v[78:79], v[86:87], v[102:103] op_sel_hi:[1,0,1]
	v_pk_fma_f32 v[76:77], v[76:77], v[86:87], v[100:101] op_sel_hi:[1,0,1]
	v_pk_fma_f32 v[74:75], v[74:75], v[86:87], v[98:99] op_sel_hi:[1,0,1]
	v_pk_fma_f32 v[72:73], v[72:73], v[86:87], v[92:93] op_sel_hi:[1,0,1]
	v_pk_fma_f32 v[70:71], v[70:71], v[86:87], v[90:91] op_sel_hi:[1,0,1]
	v_pk_mul_f32 v[86:87], v[82:83], s[84:85] op_sel_hi:[1,0]
	s_nop 0
	v_exp_f32_e32 v86, v86
	v_exp_f32_e32 v87, v87
	s_nop 0
	v_pk_add_f32 v[86:87], v[86:87], 1.0 op_sel_hi:[1,0]
	s_nop 0
	v_rcp_f32_e32 v86, v86
	v_rcp_f32_e32 v87, v87
	s_nop 0
	v_pk_mul_f32 v[82:83], v[82:83], v[86:87]
	s_nop 0
	v_pk_mul_f32 v[74:75], v[74:75], v[82:83]
	v_pk_mul_f32 v[82:83], v[84:85], s[84:85] op_sel_hi:[1,0]
	s_nop 0
	v_exp_f32_e32 v82, v82
	v_exp_f32_e32 v83, v83
	s_nop 0
	v_pk_add_f32 v[82:83], v[82:83], 1.0 op_sel_hi:[1,0]
	s_nop 0
	v_rcp_f32_e32 v82, v82
	v_rcp_f32_e32 v83, v83
	s_nop 0
	v_pk_mul_f32 v[82:83], v[84:85], v[82:83]
	s_nop 0
	v_pk_mul_f32 v[76:77], v[76:77], v[82:83]
	v_pk_mul_f32 v[82:83], v[78:79], s[84:85] op_sel_hi:[1,0]
	s_nop 0
	v_exp_f32_e32 v82, v82
	v_exp_f32_e32 v83, v83
	s_nop 0
	v_pk_add_f32 v[82:83], v[82:83], 1.0 op_sel_hi:[1,0]
	s_nop 0
	v_rcp_f32_e32 v82, v82
	v_rcp_f32_e32 v83, v83
	s_nop 0
	v_pk_mul_f32 v[78:79], v[78:79], v[82:83]
	s_nop 0
	v_pk_mul_f32 v[78:79], v[70:71], v[78:79]
	v_pk_mul_f32 v[70:71], v[80:81], s[84:85] op_sel_hi:[1,0]
	s_nop 0
	v_exp_f32_e32 v70, v70
	v_exp_f32_e32 v71, v71
	s_nop 0
	v_pk_add_f32 v[70:71], v[70:71], 1.0 op_sel_hi:[1,0]
	s_nop 0
	v_rcp_f32_e32 v70, v70
	v_rcp_f32_e32 v71, v71
	s_nop 0
	v_pk_mul_f32 v[70:71], v[80:81], v[70:71]
	s_nop 0
	v_pk_mul_f32 v[80:81], v[72:73], v[70:71]
; __device__ __forceinline__ unsigned cvt_pk_bf16(float lo, float hi) { unsigned r; asm volatile("v_cvt_pk_bf16_f32 %0, %1, %2" : "=v"(r) : "v"(lo), "v"(hi)); return r; }
; #define PG8_GPTR(p) ((__attribute__((address_space(1))) char*)(p))
; __device__ __forceinline__ f32x2 swiglu_pk(f32x2 g, f32x2 u) {
;     const f32x2 t = g * (-LOG2E); f32x2 e; e.x = __builtin_amdgcn_exp2f(t.x); e.y = __builtin_amdgcn_exp2f(t.y);
;     const f32x2 d = e + 1.0f; f32x2 r; r.x = __builtin_amdgcn_rcpf(d.x); r.y = __builtin_amdgcn_rcpf(d.y);
;     return (g * r) * u;
; }
;     __device__ __forceinline__ void operator()(const f32x4 (&acc)[2][2][4][2], const Unit& u, int wr, int wc, int fr, int fq, int par, PG8_LAS unsigned char* lds) const {
;     ...
;             for (int m = 0; m < 4; ++m) {
;                 const int row = row0 + ai * HALF + m * 16;
;                 const float rs = rsv[ai * 4 + m];
;                 const f32x4 g0 = acc[ai][0][m][0] * rs + sg0, g1 = acc[ai][0][m][1] * rs + sg1, u0 = acc[ai][1][m][0] * rs + su0, u1 = acc[ai][1][m][1] * rs + su1;
;                 f32x4 h0, h1;
;                 { const f32x2 a = swiglu_pk((f32x2){g0[0], g0[1]}, (f32x2){u0[0], u0[1]}), b2 = swiglu_pk((f32x2){g0[2], g0[3]}, (f32x2){u0[2], u0[3]});
;                   const f32x2 c = swiglu_pk((f32x2){g1[0], g1[1]}, (f32x2){u1[0], u1[1]}), d = swiglu_pk((f32x2){g1[2], g1[3]}, (f32x2){u1[2], u1[3]});
;                   h0 = (f32x4){a.x, a.y, b2.x, b2.y}; h1 = (f32x4){c.x, c.y, d.x, d.y}; }
;                 u32x4 w; w.x = cvt_pk_bf16(h0[0], h0[1]); w.y = cvt_pk_bf16(h0[2], h0[3]); w.z = cvt_pk_bf16(h1[0], h1[1]); w.w = cvt_pk_bf16(h1[2], h1[3]);
;                 *(gs_u32x4*)(PG8_GPTR(O) + (unsigned)(row * FFN + col0) * 2u) = w;
;             }
	v_cvt_pk_bf16_f32 v70, v74, v75
	v_cvt_pk_bf16_f32 v71, v76, v77
	v_add_u32_e32 v74, 0x42000, v0
	v_cvt_pk_bf16_f32 v72, v78, v79
	v_cvt_pk_bf16_f32 v73, v80, v81
	global_store_dwordx4 v74, v[70:73], s[14:15] nt
	s_nop 1
	v_pk_mul_f32 v[70:71], v[66:67], s[84:85] op_sel_hi:[1,0]
	s_nop 0
	v_exp_f32_e32 v70, v70
	v_exp_f32_e32 v71, v71
	s_nop 0
	v_pk_add_f32 v[70:71], v[70:71], 1.0 op_sel_hi:[1,0]
	s_nop 0
	v_rcp_f32_e32 v70, v70
	v_rcp_f32_e32 v71, v71
	s_nop 0
	v_pk_mul_f32 v[66:67], v[66:67], v[70:71]
	s_nop 0
	v_pk_mul_f32 v[58:59], v[58:59], v[66:67]
	v_pk_mul_f32 v[66:67], v[68:69], s[84:85] op_sel_hi:[1,0]
	s_nop 0
	v_exp_f32_e32 v66, v66
	v_exp_f32_e32 v67, v67
	s_nop 0
	v_pk_add_f32 v[66:67], v[66:67], 1.0 op_sel_hi:[1,0]
	s_nop 0
	v_rcp_f32_e32 v66, v66
	v_rcp_f32_e32 v67, v67
	s_nop 0
	v_pk_mul_f32 v[66:67], v[68:69], v[66:67]
	s_nop 0
	v_pk_mul_f32 v[60:61], v[60:61], v[66:67]
	v_pk_mul_f32 v[66:67], v[62:63], s[84:85] op_sel_hi:[1,0]
	s_nop 0
	v_exp_f32_e32 v66, v66
	v_exp_f32_e32 v67, v67
	s_nop 0
	v_pk_add_f32 v[66:67], v[66:67], 1.0 op_sel_hi:[1,0]
	s_nop 0
	v_rcp_f32_e32 v66, v66
	v_rcp_f32_e32 v67, v67
	s_nop 0
	v_pk_mul_f32 v[62:63], v[62:63], v[66:67]
	s_nop 0
	v_pk_mul_f32 v[62:63], v[54:55], v[62:63]
	v_pk_mul_f32 v[54:55], v[64:65], s[84:85] op_sel_hi:[1,0]
	s_nop 0
	v_exp_f32_e32 v54, v54
	v_exp_f32_e32 v55, v55
	s_nop 0
	v_pk_add_f32 v[54:55], v[54:55], 1.0 op_sel_hi:[1,0]
	s_nop 0
	v_rcp_f32_e32 v54, v54
	v_rcp_f32_e32 v55, v55
	s_nop 0
	v_pk_mul_f32 v[54:55], v[64:65], v[54:55]
	s_nop 0
	v_pk_mul_f32 v[64:65], v[56:57], v[54:55]
	v_cvt_pk_bf16_f32 v54, v58, v59
	v_add_u32_e32 v58, 0xb0000, v0
	v_cvt_pk_bf16_f32 v55, v60, v61
	v_cvt_pk_bf16_f32 v56, v62, v63
	v_cvt_pk_bf16_f32 v57, v64, v65
	global_store_dwordx4 v58, v[54:57], s[14:15] nt
	s_nop 1
	v_mov_b32_e32 v54, v163
	v_pk_fma_f32 v[50:51], v[50:51], v[54:55], v[106:107] op_sel_hi:[1,0,1]
	v_pk_fma_f32 v[52:53], v[52:53], v[54:55], v[108:109] op_sel_hi:[1,0,1]
	v_pk_fma_f32 v[48:49], v[48:49], v[54:55], v[104:105] op_sel_hi:[1,0,1]
	v_pk_fma_f32 v[46:47], v[46:47], v[54:55], v[102:103] op_sel_hi:[1,0,1]
	v_pk_fma_f32 v[44:45], v[44:45], v[54:55], v[100:101] op_sel_hi:[1,0,1]
	v_pk_fma_f32 v[42:43], v[42:43], v[54:55], v[98:99] op_sel_hi:[1,0,1]
	v_pk_fma_f32 v[40:41], v[40:41], v[54:55], v[92:93] op_sel_hi:[1,0,1]
	v_pk_fma_f32 v[38:39], v[38:39], v[54:55], v[90:91] op_sel_hi:[1,0,1]
	v_pk_mul_f32 v[54:55], v[50:51], s[84:85] op_sel_hi:[1,0]
	s_nop 0
	v_exp_f32_e32 v54, v54
	v_exp_f32_e32 v55, v55
	s_nop 0
	v_pk_add_f32 v[54:55], v[54:55], 1.0 op_sel_hi:[1,0]
	s_nop 0
	v_rcp_f32_e32 v54, v54
	v_rcp_f32_e32 v55, v55
	s_nop 0
	v_pk_mul_f32 v[50:51], v[50:51], v[54:55]
	s_nop 0
	v_pk_mul_f32 v[42:43], v[42:43], v[50:51]
	v_pk_mul_f32 v[50:51], v[52:53], s[84:85] op_sel_hi:[1,0]
	s_nop 0
	v_exp_f32_e32 v50, v50
	v_exp_f32_e32 v51, v51
	s_nop 0
	v_pk_add_f32 v[50:51], v[50:51], 1.0 op_sel_hi:[1,0]
	s_nop 0
	v_rcp_f32_e32 v50, v50
	v_rcp_f32_e32 v51, v51
	s_nop 0
	v_pk_mul_f32 v[50:51], v[52:53], v[50:51]
	s_nop 0
	v_pk_mul_f32 v[44:45], v[44:45], v[50:51]
	v_pk_mul_f32 v[50:51], v[46:47], s[84:85] op_sel_hi:[1,0]
	s_nop 0
	v_exp_f32_e32 v50, v50
	v_exp_f32_e32 v51, v51
	s_nop 0
	v_pk_add_f32 v[50:51], v[50:51], 1.0 op_sel_hi:[1,0]
	s_nop 0
	v_rcp_f32_e32 v50, v50
	v_rcp_f32_e32 v51, v51
	s_nop 0
	v_pk_mul_f32 v[46:47], v[46:47], v[50:51]
	s_nop 0
	v_pk_mul_f32 v[46:47], v[38:39], v[46:47]
	v_pk_mul_f32 v[38:39], v[48:49], s[84:85] op_sel_hi:[1,0]
	s_nop 0
	v_exp_f32_e32 v38, v38
	v_exp_f32_e32 v39, v39
	s_nop 0
	v_pk_add_f32 v[38:39], v[38:39], 1.0 op_sel_hi:[1,0]
	s_nop 0
	v_rcp_f32_e32 v38, v38
	v_rcp_f32_e32 v39, v39
	s_nop 0
	v_pk_mul_f32 v[38:39], v[48:49], v[38:39]
	s_nop 0
	v_pk_mul_f32 v[48:49], v[40:41], v[38:39]
	v_cvt_pk_bf16_f32 v38, v42, v43
	v_cvt_pk_bf16_f32 v39, v44, v45
	v_add_u32_e32 v42, 0xc6000, v0
	v_cvt_pk_bf16_f32 v40, v46, v47
; __device__ __forceinline__ unsigned cvt_pk_bf16(float lo, float hi) { unsigned r; asm volatile("v_cvt_pk_bf16_f32 %0, %1, %2" : "=v"(r) : "v"(lo), "v"(hi)); return r; }
; #define PG8_GPTR(p) ((__attribute__((address_space(1))) char*)(p))
;     __device__ __forceinline__ void operator()(const f32x4 (&acc)[2][2][4][2], const Unit& u, int wr, int wc, int fr, int fq, int par, PG8_LAS unsigned char* lds) const {
;     ...
;             for (int m = 0; m < 4; ++m) {
;                 const int row = row0 + ai * HALF + m * 16;
;                 const float rs = rsv[ai * 4 + m];
;                 const f32x4 g0 = acc[ai][0][m][0] * rs + sg0, g1 = acc[ai][0][m][1] * rs + sg1, u0 = acc[ai][1][m][0] * rs + su0, u1 = acc[ai][1][m][1] * rs + su1;
;                 f32x4 h0, h1;
;                 { const f32x2 a = swiglu_pk((f32x2){g0[0], g0[1]}, (f32x2){u0[0], u0[1]}), b2 = swiglu_pk((f32x2){g0[2], g0[3]}, (f32x2){u0[2], u0[3]});
;                   const f32x2 c = swiglu_pk((f32x2){g1[0], g1[1]}, (f32x2){u1[0], u1[1]}), d = swiglu_pk((f32x2){g1[2], g1[3]}, (f32x2){u1[2], u1[3]});
;                   h0 = (f32x4){a.x, a.y, b2.x, b2.y}; h1 = (f32x4){c.x, c.y, d.x, d.y}; }
;                 u32x4 w; w.x = cvt_pk_bf16(h0[0], h0[1]); w.y = cvt_pk_bf16(h0[2], h0[3]); w.z = cvt_pk_bf16(h1[0], h1[1]); w.w = cvt_pk_bf16(h1[2], h1[3]);
;                 *(gs_u32x4*)(PG8_GPTR(O) + (unsigned)(row * FFN + col0) * 2u) = w;
;             }
	v_cvt_pk_bf16_f32 v41, v48, v49
	global_store_dwordx4 v42, v[38:41], s[14:15] nt
	s_nop 1
	v_pk_mul_f32 v[38:39], v[34:35], s[84:85] op_sel_hi:[1,0]
	s_nop 0
	v_exp_f32_e32 v38, v38
	v_exp_f32_e32 v39, v39
	s_nop 0
	v_pk_add_f32 v[38:39], v[38:39], 1.0 op_sel_hi:[1,0]
	s_nop 0
	v_rcp_f32_e32 v38, v38
	v_rcp_f32_e32 v39, v39
	s_nop 0
	v_pk_mul_f32 v[34:35], v[34:35], v[38:39]
	s_nop 0
	v_pk_mul_f32 v[26:27], v[26:27], v[34:35]
	v_pk_mul_f32 v[34:35], v[36:37], s[84:85] op_sel_hi:[1,0]
	s_nop 0
	v_exp_f32_e32 v34, v34
	v_exp_f32_e32 v35, v35
	s_nop 0
	v_pk_add_f32 v[34:35], v[34:35], 1.0 op_sel_hi:[1,0]
	s_nop 0
	v_rcp_f32_e32 v34, v34
	v_rcp_f32_e32 v35, v35
	s_nop 0
	v_pk_mul_f32 v[34:35], v[36:37], v[34:35]
	s_nop 0
	v_pk_mul_f32 v[28:29], v[28:29], v[34:35]
	v_pk_mul_f32 v[34:35], v[30:31], s[84:85] op_sel_hi:[1,0]
	s_nop 0
	v_exp_f32_e32 v34, v34
	v_exp_f32_e32 v35, v35
	s_nop 0
	v_pk_add_f32 v[34:35], v[34:35], 1.0 op_sel_hi:[1,0]
	s_nop 0
	v_rcp_f32_e32 v34, v34
	v_rcp_f32_e32 v35, v35
	s_nop 0
	v_pk_mul_f32 v[30:31], v[30:31], v[34:35]
	s_nop 0
	v_pk_mul_f32 v[30:31], v[22:23], v[30:31]
	v_pk_mul_f32 v[22:23], v[32:33], s[84:85] op_sel_hi:[1,0]
	s_nop 0
	v_exp_f32_e32 v22, v22
	v_exp_f32_e32 v23, v23
	s_nop 0
	v_pk_add_f32 v[22:23], v[22:23], 1.0 op_sel_hi:[1,0]
	s_nop 0
	v_rcp_f32_e32 v22, v22
	v_rcp_f32_e32 v23, v23
	s_nop 0
	v_pk_mul_f32 v[22:23], v[32:33], v[22:23]
	s_nop 0
	v_pk_mul_f32 v[32:33], v[24:25], v[22:23]
	v_cvt_pk_bf16_f32 v22, v26, v27
	v_add_u32_e32 v26, 0xdc000, v0
	v_cvt_pk_bf16_f32 v23, v28, v29
	v_cvt_pk_bf16_f32 v24, v30, v31
	v_cvt_pk_bf16_f32 v25, v32, v33
	global_store_dwordx4 v26, v[22:25], s[14:15] nt
	v_add_u32_e32 v0, 0xf2000, v0
	s_nop 0
	v_mov_b32_e32 v22, v161
	v_pk_fma_f32 v[18:19], v[18:19], v[22:23], v[106:107] op_sel_hi:[1,0,1]
	v_pk_fma_f32 v[20:21], v[20:21], v[22:23], v[108:109] op_sel_hi:[1,0,1]
	v_pk_fma_f32 v[12:13], v[12:13], v[22:23], v[104:105] op_sel_hi:[1,0,1]
	v_pk_fma_f32 v[10:11], v[10:11], v[22:23], v[102:103] op_sel_hi:[1,0,1]
	v_pk_fma_f32 v[8:9], v[8:9], v[22:23], v[100:101] op_sel_hi:[1,0,1]
	v_pk_fma_f32 v[6:7], v[6:7], v[22:23], v[98:99] op_sel_hi:[1,0,1]
	v_pk_fma_f32 v[4:5], v[4:5], v[22:23], v[92:93] op_sel_hi:[1,0,1]
	v_pk_fma_f32 v[2:3], v[2:3], v[22:23], v[90:91] op_sel_hi:[1,0,1]
	v_pk_mul_f32 v[22:23], v[18:19], s[84:85] op_sel_hi:[1,0]
	s_nop 0
	v_exp_f32_e32 v22, v22
	v_exp_f32_e32 v23, v23
	s_nop 0
	v_pk_add_f32 v[22:23], v[22:23], 1.0 op_sel_hi:[1,0]
	s_nop 0
	v_rcp_f32_e32 v22, v22
	v_rcp_f32_e32 v23, v23
	s_nop 0
	v_pk_mul_f32 v[18:19], v[18:19], v[22:23]
	s_nop 0
	v_pk_mul_f32 v[6:7], v[6:7], v[18:19]
	v_pk_mul_f32 v[18:19], v[20:21], s[84:85] op_sel_hi:[1,0]
	s_nop 0
	v_exp_f32_e32 v18, v18
	v_exp_f32_e32 v19, v19
	s_nop 0
	v_pk_add_f32 v[18:19], v[18:19], 1.0 op_sel_hi:[1,0]
	s_nop 0
	v_rcp_f32_e32 v18, v18
	v_rcp_f32_e32 v19, v19
	s_nop 0
	v_pk_mul_f32 v[18:19], v[20:21], v[18:19]
	s_nop 0
	v_pk_mul_f32 v[8:9], v[8:9], v[18:19]
	v_pk_mul_f32 v[18:19], v[10:11], s[84:85] op_sel_hi:[1,0]
	s_nop 0
	v_exp_f32_e32 v18, v18
	v_exp_f32_e32 v19, v19
	s_nop 0
	v_pk_add_f32 v[18:19], v[18:19], 1.0 op_sel_hi:[1,0]
	s_nop 0
	v_rcp_f32_e32 v18, v18
	v_rcp_f32_e32 v19, v19
	s_nop 0
	v_pk_mul_f32 v[10:11], v[10:11], v[18:19]
	s_nop 0
	v_pk_mul_f32 v[10:11], v[2:3], v[10:11]
	v_pk_mul_f32 v[2:3], v[12:13], s[84:85] op_sel_hi:[1,0]
	s_nop 0
	v_exp_f32_e32 v2, v2
	v_exp_f32_e32 v3, v3
	s_nop 0
	v_pk_add_f32 v[2:3], v[2:3], 1.0 op_sel_hi:[1,0]
	s_nop 0
	v_rcp_f32_e32 v2, v2
	v_rcp_f32_e32 v3, v3
	s_nop 0
	v_pk_mul_f32 v[2:3], v[12:13], v[2:3]
	s_nop 0
	v_pk_mul_f32 v[12:13], v[4:5], v[2:3]
	v_cvt_pk_bf16_f32 v2, v6, v7
	v_cvt_pk_bf16_f32 v3, v8, v9
	v_cvt_pk_bf16_f32 v4, v10, v11
	s_nop 0
	v_cvt_pk_bf16_f32 v5, v12, v13
	global_store_dwordx4 v0, v[2:5], s[14:15] nt
	s_cbranch_vccnz .LBB0_1161
	s_andn2_b64 vcc, exec, s[12:13]
	s_cbranch_vccnz .LBB0_1160
	s_barrier
	s_branch .LBB0_1160
